# phase-local wave priority raise inside the VALU-bound conv/SiLU epilogue loop of up (s_setprio 2 at loop entry, 0 at exit), on top of the four-tail GEMM version
# baseline (speedup 1.0000x reference)
; #define WAIT_V0() asm volatile("s_waitcnt vmcnt(0)" ::: "memory")
; DI int glds_row(int i) { const int tid = ltid(); return ((tid >> 6) * 4 + i) * 8 + ((tid & 63) >> 3); }
; DI int glds_chunk(int row) { return (ltid() & 7) ^ ((row >> 1) & 7); }
; DI void gemm_core(char* smem, int nk, const char* Ab, const char* Bb, const unsigned (&aoff)[4], const unsigned (&boff)[4],
;                   f32x16 (&acc)[2][2]) {
;     ...
;   auto stage = [&](int buf, int kt) __attribute__((always_inline)) {
;     const char* ak = Ab + kt * 128;
;     const char* bk = Bb + kt * 128;
;     char* sa = smem + buf * STAGE_B + w * 4096;
; #pragma unroll
;     for (int i = 0; i < 4; ++i) {
;       __builtin_amdgcn_global_load_lds((const unsigned*)(ak + aoff[i]), (unsigned*)(sa + i * 1024), 16, 0, 0);
;       __builtin_amdgcn_global_load_lds((const unsigned*)(bk + boff[i]), (unsigned*)(sa + 16384 + i * 1024), 16, 0, 0);
;     }
;   };
;   stage(0, 0);
;   WAIT_V0();
;   __syncthreads();
; DI void phase_up(const Params& P, int layer, char* smem) {
;     ...
;   for (int t0 = blockIdx.x; t0 < MT * NT; t0 += gridDim.x) {
;     const int tl = xcd_tile(t0, MT * NT) - (t0 & 7) * ((MT * NT) >> 3);
;     const int mt = (t0 & 1) * 131 + tl / 11, nt = ((t0 & 7) >> 1) * 11 + tl % 11;
;     const int b = mt / 131, i = mt % 131;
;     const int tb0 = i * 126 - 2;
;     unsigned aoff[4], boff[4];
;     const char* Abase = (const char*)(hn + (size_t)b * S_ * 1024);
;     const unsigned zoff = (unsigned)((P.ws + OFF_ZPAGE) - Abase);
; #pragma unroll
;     for (int q = 0; q < 4; ++q) {
;       const int r = glds_row(q), ch = glds_chunk(r);
;       const int tb = tb0 + r;
;       const bool ok = (tb >= 0) && (tb < S_);
;       aoff[q] = ok ? (unsigned)((tb * 1024 + ch * 8) * 2) : zoff;
;       const int wr = (r < 64) ? (nt * 64 + r) : (DFF + nt * 64 + r - 64);
;       boff[q] = (unsigned)((wr * 1024 + ch * 8) * 2);
;     }
;     f32x16 acc[2][2];
;     gemm_core(smem, 16, Abase, (const char*)wup, aoff, boff, acc);
.LBB0_25:
	s_ashr_i32 s18, s2, 3
	s_and_b32 s19, s18, 0xffffffc0
	s_lshl_b32 s20, s18, 1
	s_bfe_u32 s21, s18, 0x10005
	s_and_b32 s20, s20, 62
	s_or_b32 s19, s21, s19
	s_or_b32 s19, s19, s20
	s_or_b32 s20, s18, 63
	s_cmpk_lt_i32 s20, 0x5a1
	s_cselect_b32 s18, s19, s18
	s_bitcmp1_b32 s2, 0
	s_mul_hi_i32 s20, s18, 0x2e8ba2e9
	s_cselect_b32 s19, 0x83, 0
	s_lshr_b32 s21, s20, 31
	s_ashr_i32 s20, s20, 1
	s_add_i32 s21, s20, s21
	s_add_i32 s20, s21, s19
	s_bfe_u32 s19, s2, 0x20001
	s_mul_i32 s21, s21, 11
	s_mul_i32 s19, s19, 11
	s_sub_i32 s18, s18, s21
	s_add_i32 s21, s18, s19
	s_mul_hi_i32 s18, s20, 0x3e88cb3d
	s_lshr_b32 s19, s18, 31
	s_ashr_i32 s18, s18, 5
	v_mov_b32_e32 v0, v161
	s_add_i32 s68, s18, s19
	s_mul_i32 s18, s68, 0x83
	v_ashrrev_i32_e32 v1, 1, v0
	v_lshrrev_b32_e32 v2, 3, v0
	v_bfe_u32 v0, v0, 3, 3
	s_movk_i32 s3, 0xffe0
	s_sub_i32 s28, s20, s18
	v_and_or_b32 v0, v1, s3, v0
	v_mov_b32_e32 v1, v161
	s_mulk_i32 s28, 0x7e
	s_ashr_i32 s69, s68, 31
	v_bfe_u32 v2, v2, 1, 2
	s_add_i32 s29, s28, -2
	s_lshl_b64 s[22:23], s[68:69], 25
	v_xor_b32_e32 v1, v2, v1
	s_add_u32 s18, s84, s22
	v_lshlrev_b32_e32 v1, 4, v1
	s_addc_u32 s19, s85, s23
	s_sub_i32 s22, 0x1b508000, s22
	s_lshl_b32 s21, s21, 6
	v_add_u32_e32 v2, s29, v0
	v_and_b32_e32 v1, 0x70, v1
	s_movk_i32 s3, 0x4000
	s_add_i32 s23, s21, 0xac0
	v_lshl_or_b32 v3, v2, 11, v1
	v_mov_b32_e32 v4, s22
	v_cmp_gt_u32_e32 vcc, s3, v2
	v_mov_b32_e32 v5, s21
	v_mov_b32_e32 v12, v161
	v_cndmask_b32_e32 v136, v4, v3, vcc
	v_mov_b32_e32 v3, s23
	v_cmp_gt_i32_e32 vcc, 64, v0
	v_lshl_add_u64 v[64:65], s[18:19], 0, v[136:137]
	s_mov_b64 s[4:5], 0x100
	v_cndmask_b32_e32 v2, v3, v5, vcc
	v_add_u32_e32 v0, v2, v0
	v_lshl_or_b32 v76, v0, 11, v1
	v_mov_b32_e32 v0, v161
	s_mov_b64 s[6:7], 0x780
	v_ashrrev_i32_e32 v1, 1, v0
	v_and_b32_e32 v1, 0xffffffe0, v1
	v_bfe_u32 v0, v0, 3, 3
	v_or3_b32 v1, v1, v0, 8
	v_mov_b32_e32 v0, v161
	v_lshrrev_b32_e32 v2, 1, v1
	v_xor_b32_e32 v0, v2, v0
	v_lshlrev_b32_e32 v0, 4, v0
	v_add_u32_e32 v2, s29, v1
	v_and_b32_e32 v6, 0x70, v0
	v_lshl_or_b32 v0, v2, 11, v6
	v_cmp_gt_u32_e32 vcc, s3, v2
	s_nop 1
	v_cndmask_b32_e32 v0, v4, v0, vcc
	v_cmp_gt_i32_e32 vcc, 64, v1
	s_nop 1
	v_cndmask_b32_e32 v2, v3, v5, vcc
	v_add_u32_e32 v1, v2, v1
	v_lshl_or_b32 v77, v1, 11, v6
	v_mov_b32_e32 v1, v161
	s_nop 0
	v_ashrrev_i32_e32 v2, 1, v1
	v_and_b32_e32 v2, 0xffffffe0, v2
	v_lshrrev_b32_e32 v6, 3, v1
	v_bfe_u32 v1, v1, 3, 3
	v_or3_b32 v1, v2, v1, 16
	v_mov_b32_e32 v2, v161
	v_bfe_u32 v6, v6, 1, 2
	v_xor_b32_e32 v2, v6, v2
	v_lshlrev_b32_e32 v2, 4, v2
	v_add_u32_e32 v6, s29, v1
	v_and_b32_e32 v7, 0x70, v2
	v_lshl_or_b32 v2, v6, 11, v7
	v_cmp_gt_u32_e32 vcc, s3, v6
	s_nop 1
	v_cndmask_b32_e32 v2, v4, v2, vcc
	v_cmp_gt_i32_e32 vcc, 64, v1
	s_nop 1
	v_cndmask_b32_e32 v6, v3, v5, vcc
	v_add_u32_e32 v1, v6, v1
	v_lshl_or_b32 v78, v1, 11, v7
	v_mov_b32_e32 v1, v161
	s_nop 0
	v_ashrrev_i32_e32 v6, 1, v1
	v_and_b32_e32 v6, 0xffffffe0, v6
	v_bfe_u32 v1, v1, 3, 3
	v_or3_b32 v1, v6, v1, 24
	v_mov_b32_e32 v6, v161
	v_lshrrev_b32_e32 v7, 1, v1
	v_xor_b32_e32 v6, v7, v6
	v_lshlrev_b32_e32 v6, 4, v6
	v_add_u32_e32 v7, s29, v1
	v_and_b32_e32 v6, 0x70, v6
	v_lshl_or_b32 v8, v7, 11, v6
	v_cmp_gt_u32_e32 vcc, s3, v7
	s_mov_b32 s3, 0x1ffffc0
	v_bfe_u32 v86, v12, 1, 3
	v_cndmask_b32_e32 v4, v4, v8, vcc
	v_cmp_gt_i32_e32 vcc, 64, v1
	v_bfe_u32 v117, v12, 5, 1
	s_nop 0
	v_cndmask_b32_e32 v3, v3, v5, vcc
	v_add_u32_e32 v1, v3, v1
	v_lshl_or_b32 v84, v1, 11, v6
	v_and_b32_e32 v1, 31, v12
	v_lshrrev_b32_e32 v5, 1, v12
	v_and_or_b32 v1, v5, s3, v1
	v_lshlrev_b32_e32 v87, 7, v1
	v_lshlrev_b32_e32 v1, 6, v12
	v_and_b32_e32 v97, 0xfffff000, v1
	v_add_u32_e32 v96, 0x4000, v97
	v_readfirstlane_b32 s84, v97
	s_mov_b32 m0, s84
	v_readfirstlane_b32 s85, v96
	v_or_b32_e32 v98, 0x400, v97
	global_load_lds_dwordx4 v136, s[18:19]
	s_mov_b32 m0, s85
	v_readfirstlane_b32 s86, v98
	v_add_u32_e32 v99, 0x4400, v97
	global_load_lds_dwordx4 v76, s[0:1]
	s_mov_b32 m0, s86
	v_readfirstlane_b32 s87, v99
	v_or_b32_e32 v100, 0x800, v97
	global_load_lds_dwordx4 v0, s[18:19]
	s_mov_b32 m0, s87
	v_readfirstlane_b32 s88, v100
	v_add_u32_e32 v101, 0x4800, v97
	v_lshrrev_b32_e32 v3, 5, v12
	global_load_lds_dwordx4 v77, s[0:1]
	s_mov_b32 m0, s88
	v_readfirstlane_b32 s89, v101
	v_or_b32_e32 v102, 0xc00, v97
	v_bitop3_b32 v3, v3, v86, 1 bitop3:0x6c
	global_load_lds_dwordx4 v2, s[18:19]
	s_mov_b32 m0, s89
	v_readfirstlane_b32 s90, v102
	v_add_u32_e32 v103, 0x4c00, v97
	v_lshlrev_b32_e32 v6, 4, v3
	v_mov_b32_e32 v1, v137
	v_mov_b32_e32 v3, v137
	global_load_lds_dwordx4 v78, s[0:1]
	v_mov_b32_e32 v5, v137
	s_mov_b32 m0, s90
	v_readfirstlane_b32 s91, v103
	v_add_u32_e32 v89, 0x8000, v97
	v_lshl_add_u64 v[66:67], s[18:19], 0, v[0:1]
	v_lshl_add_u64 v[68:69], s[18:19], 0, v[2:3]
	v_lshl_add_u64 v[70:71], s[18:19], 0, v[4:5]
	global_load_lds_dwordx4 v4, s[18:19]
	s_mov_b32 m0, s91
	v_add_u32_e32 v88, 0xc000, v97
	v_readfirstlane_b32 s18, v89
	global_load_lds_dwordx4 v84, s[0:1]
	v_lshl_add_u64 v[0:1], v[64:65], 0, s[94:95]
	s_mov_b32 m0, s18
	v_readfirstlane_b32 s19, v88
	v_add_u32_e32 v90, 0x8400, v97
	global_load_lds_dwordx4 v[0:1], off
	s_mov_b32 m0, s19
	v_readfirstlane_b32 s22, v90
	v_add_u32_e32 v91, 0xc400, v97
	global_load_lds_dwordx4 v76, s[14:15]
	v_lshl_add_u64 v[0:1], v[66:67], 0, s[94:95]
	s_mov_b32 m0, s22
	v_readfirstlane_b32 s23, v91
	v_add_u32_e32 v92, 0x8800, v97
	global_load_lds_dwordx4 v[0:1], off
	s_mov_b32 m0, s23
	v_readfirstlane_b32 s29, v92
	v_add_u32_e32 v93, 0xc800, v97
	global_load_lds_dwordx4 v77, s[14:15]
	v_lshl_add_u64 v[0:1], v[68:69], 0, s[94:95]
	s_mov_b32 m0, s29
	v_readfirstlane_b32 s69, v93
	v_add_u32_e32 v94, 0x8c00, v97
	global_load_lds_dwordx4 v[0:1], off
	s_mov_b32 m0, s69
	v_readfirstlane_b32 s70, v94
	v_add_u32_e32 v95, 0xcc00, v97
	global_load_lds_dwordx4 v78, s[14:15]
	v_lshl_add_u64 v[0:1], v[70:71], 0, s[94:95]
	s_mov_b32 m0, s70
	v_readfirstlane_b32 s71, v95
	global_load_lds_dwordx4 v[0:1], off
	s_mov_b32 m0, s71
	v_or_b32_e32 v79, v87, v6
	global_load_lds_dwordx4 v84, s[14:15]
	s_waitcnt vmcnt(8)
	s_waitcnt vmcnt(8) lgkmcnt(0)
	s_barrier
; #define WAIT_V0() asm volatile("s_waitcnt vmcnt(0)" ::: "memory")
; DI void gemm_core(char* smem, int nk, const char* Ab, const char* Bb, const unsigned (&aoff)[4], const unsigned (&boff)[4],
;                   f32x16 (&acc)[2][2]) {
;     ...
;   auto stage = [&](int buf, int kt) __attribute__((always_inline)) {
;     const char* ak = Ab + kt * 128;
;     const char* bk = Bb + kt * 128;
;     char* sa = smem + buf * STAGE_B + w * 4096;
; #pragma unroll
;     for (int i = 0; i < 4; ++i) {
;       __builtin_amdgcn_global_load_lds((const unsigned*)(ak + aoff[i]), (unsigned*)(sa + i * 1024), 16, 0, 0);
;       __builtin_amdgcn_global_load_lds((const unsigned*)(bk + boff[i]), (unsigned*)(sa + 16384 + i * 1024), 16, 0, 0);
;     }
;   };
;   stage(0, 0);
;   WAIT_V0();
;   __syncthreads();
;   for (int kt = 0; kt < nk; ++kt) {
;     const int cur = kt & 1;
;     if (kt + 1 < nk) stage(cur ^ 1, kt + 1);
;     const char* sb = smem + cur * STAGE_B;
; #pragma unroll
;     for (int ks = 0; ks < 4; ++ks) {
;       bf16x8 af[2], bfr[2];
; #pragma unroll
;       for (int mb = 0; mb < 2; ++mb) af[mb] = *(const bf16x8*)(sb + a_base + mb * 4096 + xo[ks]);
; #pragma unroll
;       for (int nb = 0; nb < 2; ++nb) bfr[nb] = *(const bf16x8*)(sb + b_base + nb * 4096 + xo[ks]);
; #pragma unroll
;       for (int mb = 0; mb < 2; ++mb)
; #pragma unroll
;         for (int nb = 0; nb < 2; ++nb)
;           acc[mb][nb] = __builtin_amdgcn_mfma_f32_32x32x16_bf16(af[mb], bfr[nb], acc[mb][nb], 0, 0, 0);
;     }
;     WAIT_V0();
;     __syncthreads();
;   }
	ds_read_b128 v[0:3], v79
	v_lshlrev_b32_e32 v4, 7, v12
	v_and_b32_e32 v116, 0x2f80, v4
	v_or_b32_e32 v81, v116, v6
	ds_read_b128 v[4:7], v81 offset:16384
	ds_read_b128 v[8:11], v81 offset:20480
	s_waitcnt lgkmcnt(0)
	v_mfma_f32_32x32x16_bf16 v[48:63], v[0:3], v[4:7], 0
	s_mov_b32 m0, s84
	s_mov_b32 s3, 0xfffffc0
	v_mfma_f32_32x32x16_bf16 v[32:47], v[0:3], v[8:11], 0
	ds_read_b128 v[0:3], v79 offset:4096
	s_waitcnt lgkmcnt(0)
	v_mfma_f32_32x32x16_bf16 v[16:31], v[0:3], v[4:7], 0
	v_bitop3_b32 v4, v117, v86, 2 bitop3:0x36
	v_lshlrev_b32_e32 v82, 4, v4
	v_or_b32_e32 v80, v87, v82
	ds_read_b128 v[104:107], v80
	v_or_b32_e32 v83, v116, v82
	ds_read_b128 v[108:111], v83 offset:16384
	ds_read_b128 v[112:115], v83 offset:20480
	s_waitcnt lgkmcnt(0)
	v_mfma_f32_32x32x16_bf16 v[48:63], v[104:107], v[108:111], v[48:63]
	v_bitop3_b32 v82, v117, v86, 4 bitop3:0x36
	v_lshlrev_b32_e32 v85, 4, v82
	v_or_b32_e32 v82, v87, v85
	v_or_b32_e32 v85, v116, v85
	v_bitop3_b32 v86, v117, v86, 6 bitop3:0x36
	v_mfma_f32_32x32x16_bf16 v[32:47], v[104:107], v[112:115], v[32:47]
	ds_read_b128 v[104:107], v80 offset:4096
	v_mfma_f32_32x32x16_bf16 v[0:15], v[0:3], v[8:11], 0
	s_waitcnt lgkmcnt(0)
	v_mfma_f32_32x32x16_bf16 v[16:31], v[104:107], v[108:111], v[16:31]
	ds_read_b128 v[108:111], v85 offset:16384
	v_mfma_f32_32x32x16_bf16 v[0:15], v[104:107], v[112:115], v[0:15]
	ds_read_b128 v[104:107], v82
	ds_read_b128 v[112:115], v85 offset:20480
	s_waitcnt lgkmcnt(0)
	v_mfma_f32_32x32x16_bf16 v[48:63], v[104:107], v[108:111], v[48:63]
	v_mfma_f32_32x32x16_bf16 v[32:47], v[104:107], v[112:115], v[32:47]
	ds_read_b128 v[104:107], v82 offset:4096
	s_waitcnt lgkmcnt(0)
	v_mfma_f32_32x32x16_bf16 v[16:31], v[104:107], v[108:111], v[16:31]
	v_lshlrev_b32_e32 v108, 4, v86
	v_or_b32_e32 v86, v87, v108
	v_or_b32_e32 v87, v116, v108
	ds_read_b128 v[108:111], v87 offset:16384
	v_mfma_f32_32x32x16_bf16 v[0:15], v[104:107], v[112:115], v[0:15]
	ds_read_b128 v[104:107], v86
	ds_read_b128 v[112:115], v87 offset:20480
	ds_read_b128 v[144:147], v86 offset:4096
	s_waitcnt vmcnt(0)
	s_waitcnt vmcnt(0) lgkmcnt(0)
	s_barrier
	v_mfma_f32_32x32x16_bf16 v[48:63], v[104:107], v[108:111], v[48:63]
	v_mfma_f32_32x32x16_bf16 v[32:47], v[104:107], v[112:115], v[32:47]
	v_mfma_f32_32x32x16_bf16 v[16:31], v[144:147], v[108:111], v[16:31]
	v_mfma_f32_32x32x16_bf16 v[0:15], v[144:147], v[112:115], v[0:15]
	ds_read_b128 v[104:107], v79 offset:32768
	ds_read_b128 v[108:111], v81 offset:49152
	ds_read_b128 v[112:115], v81 offset:53248
	v_lshl_add_u64 v[140:141], v[64:65], 0, s[4:5]
	global_load_lds_dwordx4 v[140:141], off
	s_mov_b32 m0, s85
	v_lshl_add_u64 v[142:143], v[66:67], 0, s[4:5]
	global_load_lds_dwordx4 v76, s[16:17]
	s_mov_b32 m0, s86
	s_nop 0
	global_load_lds_dwordx4 v[142:143], off
	s_mov_b32 m0, s87
	v_lshl_add_u64 v[140:141], v[68:69], 0, s[4:5]
	global_load_lds_dwordx4 v77, s[16:17]
	s_mov_b32 m0, s88
	s_nop 0
	global_load_lds_dwordx4 v[140:141], off
	s_mov_b32 m0, s89
	v_lshl_add_u64 v[142:143], v[70:71], 0, s[4:5]
	global_load_lds_dwordx4 v78, s[16:17]
	s_mov_b32 m0, s90
	s_mov_b64 s[4:5], 0x180
	global_load_lds_dwordx4 v[142:143], off
	s_mov_b32 m0, s91
	s_nop 0
	global_load_lds_dwordx4 v84, s[16:17]
	s_waitcnt lgkmcnt(0)
	v_mfma_f32_32x32x16_bf16 v[48:63], v[104:107], v[108:111], v[48:63]
	s_mov_b32 m0, s18
	v_mfma_f32_32x32x16_bf16 v[32:47], v[104:107], v[112:115], v[32:47]
	ds_read_b128 v[104:107], v79 offset:36864
	s_waitcnt lgkmcnt(0)
	v_mfma_f32_32x32x16_bf16 v[16:31], v[104:107], v[108:111], v[16:31]
	v_mfma_f32_32x32x16_bf16 v[0:15], v[104:107], v[112:115], v[0:15]
	ds_read_b128 v[104:107], v80 offset:32768
	ds_read_b128 v[108:111], v83 offset:49152
	ds_read_b128 v[112:115], v83 offset:53248
	s_waitcnt lgkmcnt(0)
	v_mfma_f32_32x32x16_bf16 v[48:63], v[104:107], v[108:111], v[48:63]
	v_mfma_f32_32x32x16_bf16 v[32:47], v[104:107], v[112:115], v[32:47]
	ds_read_b128 v[104:107], v80 offset:36864
	s_waitcnt lgkmcnt(0)
	v_mfma_f32_32x32x16_bf16 v[16:31], v[104:107], v[108:111], v[16:31]
	v_mfma_f32_32x32x16_bf16 v[0:15], v[104:107], v[112:115], v[0:15]
	ds_read_b128 v[104:107], v82 offset:32768
	ds_read_b128 v[108:111], v85 offset:49152
	ds_read_b128 v[112:115], v85 offset:53248
	s_waitcnt lgkmcnt(0)
	v_mfma_f32_32x32x16_bf16 v[48:63], v[104:107], v[108:111], v[48:63]
	v_mfma_f32_32x32x16_bf16 v[32:47], v[104:107], v[112:115], v[32:47]
	ds_read_b128 v[104:107], v82 offset:36864
	s_waitcnt lgkmcnt(0)
	v_mfma_f32_32x32x16_bf16 v[16:31], v[104:107], v[108:111], v[16:31]
	v_mfma_f32_32x32x16_bf16 v[0:15], v[104:107], v[112:115], v[0:15]
	ds_read_b128 v[104:107], v86 offset:32768
	ds_read_b128 v[108:111], v87 offset:49152
	ds_read_b128 v[112:115], v87 offset:53248
	ds_read_b128 v[144:147], v86 offset:36864
	s_waitcnt vmcnt(0)
	s_waitcnt vmcnt(0) lgkmcnt(0)
	s_barrier
; #define WAIT_V0() asm volatile("s_waitcnt vmcnt(0)" ::: "memory")
; DI void gemm_core(char* smem, int nk, const char* Ab, const char* Bb, const unsigned (&aoff)[4], const unsigned (&boff)[4],
;                   f32x16 (&acc)[2][2]) {
;     ...
;   auto stage = [&](int buf, int kt) __attribute__((always_inline)) {
;     const char* ak = Ab + kt * 128;
;     const char* bk = Bb + kt * 128;
;     char* sa = smem + buf * STAGE_B + w * 4096;
; #pragma unroll
;     for (int i = 0; i < 4; ++i) {
;       __builtin_amdgcn_global_load_lds((const unsigned*)(ak + aoff[i]), (unsigned*)(sa + i * 1024), 16, 0, 0);
;       __builtin_amdgcn_global_load_lds((const unsigned*)(bk + boff[i]), (unsigned*)(sa + 16384 + i * 1024), 16, 0, 0);
;     }
;   };
;   stage(0, 0);
;   WAIT_V0();
;   __syncthreads();
;   for (int kt = 0; kt < nk; ++kt) {
;     const int cur = kt & 1;
;     if (kt + 1 < nk) stage(cur ^ 1, kt + 1);
;     const char* sb = smem + cur * STAGE_B;
; #pragma unroll
;     for (int ks = 0; ks < 4; ++ks) {
;       bf16x8 af[2], bfr[2];
; #pragma unroll
;       for (int mb = 0; mb < 2; ++mb) af[mb] = *(const bf16x8*)(sb + a_base + mb * 4096 + xo[ks]);
; #pragma unroll
;       for (int nb = 0; nb < 2; ++nb) bfr[nb] = *(const bf16x8*)(sb + b_base + nb * 4096 + xo[ks]);
; #pragma unroll
;       for (int mb = 0; mb < 2; ++mb)
; #pragma unroll
;         for (int nb = 0; nb < 2; ++nb)
;           acc[mb][nb] = __builtin_amdgcn_mfma_f32_32x32x16_bf16(af[mb], bfr[nb], acc[mb][nb], 0, 0, 0);
;     }
;     WAIT_V0();
;     __syncthreads();
;   }
	v_mfma_f32_32x32x16_bf16 v[48:63], v[104:107], v[108:111], v[48:63]
	v_mfma_f32_32x32x16_bf16 v[32:47], v[104:107], v[112:115], v[32:47]
	v_mfma_f32_32x32x16_bf16 v[16:31], v[144:147], v[108:111], v[16:31]
	v_mfma_f32_32x32x16_bf16 v[0:15], v[144:147], v[112:115], v[0:15]
	ds_read_b128 v[104:107], v79
	ds_read_b128 v[108:111], v81 offset:16384
	ds_read_b128 v[112:115], v81 offset:20480
	v_lshl_add_u64 v[140:141], v[64:65], 0, s[4:5]
	global_load_lds_dwordx4 v[140:141], off
	s_mov_b32 m0, s19
	v_lshl_add_u64 v[142:143], v[66:67], 0, s[4:5]
	global_load_lds_dwordx4 v76, s[42:43]
	s_mov_b32 m0, s22
	s_nop 0
	global_load_lds_dwordx4 v[142:143], off
	s_mov_b32 m0, s23
	v_lshl_add_u64 v[140:141], v[68:69], 0, s[4:5]
	global_load_lds_dwordx4 v77, s[42:43]
	s_mov_b32 m0, s29
	s_nop 0
	global_load_lds_dwordx4 v[140:141], off
	s_mov_b32 m0, s69
	v_lshl_add_u64 v[142:143], v[70:71], 0, s[4:5]
	global_load_lds_dwordx4 v78, s[42:43]
	s_mov_b32 m0, s70
	s_mov_b64 s[4:5], 0x280
	global_load_lds_dwordx4 v[142:143], off
	s_mov_b32 m0, s71
	s_nop 0
	global_load_lds_dwordx4 v84, s[42:43]
	s_waitcnt lgkmcnt(0)
	v_mfma_f32_32x32x16_bf16 v[48:63], v[104:107], v[108:111], v[48:63]
	s_mov_b32 m0, s84
	v_mfma_f32_32x32x16_bf16 v[32:47], v[104:107], v[112:115], v[32:47]
	ds_read_b128 v[104:107], v79 offset:4096
	s_waitcnt lgkmcnt(0)
	v_mfma_f32_32x32x16_bf16 v[16:31], v[104:107], v[108:111], v[16:31]
	v_mfma_f32_32x32x16_bf16 v[0:15], v[104:107], v[112:115], v[0:15]
	ds_read_b128 v[104:107], v80
	ds_read_b128 v[108:111], v83 offset:16384
	ds_read_b128 v[112:115], v83 offset:20480
	s_waitcnt lgkmcnt(0)
	v_mfma_f32_32x32x16_bf16 v[48:63], v[104:107], v[108:111], v[48:63]
	v_mfma_f32_32x32x16_bf16 v[32:47], v[104:107], v[112:115], v[32:47]
	ds_read_b128 v[104:107], v80 offset:4096
	s_waitcnt lgkmcnt(0)
	v_mfma_f32_32x32x16_bf16 v[16:31], v[104:107], v[108:111], v[16:31]
	v_mfma_f32_32x32x16_bf16 v[0:15], v[104:107], v[112:115], v[0:15]
	ds_read_b128 v[104:107], v82
	ds_read_b128 v[108:111], v85 offset:16384
	ds_read_b128 v[112:115], v85 offset:20480
	s_waitcnt lgkmcnt(0)
	v_mfma_f32_32x32x16_bf16 v[48:63], v[104:107], v[108:111], v[48:63]
	v_mfma_f32_32x32x16_bf16 v[32:47], v[104:107], v[112:115], v[32:47]
	ds_read_b128 v[104:107], v82 offset:4096
	s_waitcnt lgkmcnt(0)
	v_mfma_f32_32x32x16_bf16 v[16:31], v[104:107], v[108:111], v[16:31]
	v_mfma_f32_32x32x16_bf16 v[0:15], v[104:107], v[112:115], v[0:15]
	ds_read_b128 v[104:107], v86
	ds_read_b128 v[108:111], v87 offset:16384
	ds_read_b128 v[112:115], v87 offset:20480
	ds_read_b128 v[144:147], v86 offset:4096
	s_waitcnt vmcnt(0)
	s_waitcnt vmcnt(0) lgkmcnt(0)
	s_barrier
	v_mfma_f32_32x32x16_bf16 v[48:63], v[104:107], v[108:111], v[48:63]
	v_mfma_f32_32x32x16_bf16 v[32:47], v[104:107], v[112:115], v[32:47]
	v_mfma_f32_32x32x16_bf16 v[16:31], v[144:147], v[108:111], v[16:31]
	v_mfma_f32_32x32x16_bf16 v[0:15], v[144:147], v[112:115], v[0:15]
	ds_read_b128 v[104:107], v79 offset:32768
	ds_read_b128 v[108:111], v81 offset:49152
	ds_read_b128 v[112:115], v81 offset:53248
	v_lshl_add_u64 v[140:141], v[64:65], 0, s[30:31]
	global_load_lds_dwordx4 v[140:141], off
	s_mov_b32 m0, s85
	v_lshl_add_u64 v[142:143], v[66:67], 0, s[30:31]
	global_load_lds_dwordx4 v76, s[44:45]
	s_mov_b32 m0, s86
	s_nop 0
	global_load_lds_dwordx4 v[142:143], off
	s_mov_b32 m0, s87
	v_lshl_add_u64 v[140:141], v[68:69], 0, s[30:31]
	global_load_lds_dwordx4 v77, s[44:45]
	s_mov_b32 m0, s88
	s_nop 0
	global_load_lds_dwordx4 v[140:141], off
	s_mov_b32 m0, s89
	v_lshl_add_u64 v[142:143], v[70:71], 0, s[30:31]
	global_load_lds_dwordx4 v78, s[44:45]
	s_mov_b32 m0, s90
	s_nop 0
	global_load_lds_dwordx4 v[142:143], off
	s_mov_b32 m0, s91
	s_nop 0
	global_load_lds_dwordx4 v84, s[44:45]
	s_waitcnt lgkmcnt(0)
	v_mfma_f32_32x32x16_bf16 v[48:63], v[104:107], v[108:111], v[48:63]
	s_mov_b32 m0, s18
	v_mfma_f32_32x32x16_bf16 v[32:47], v[104:107], v[112:115], v[32:47]
	ds_read_b128 v[104:107], v79 offset:36864
	s_waitcnt lgkmcnt(0)
	v_mfma_f32_32x32x16_bf16 v[16:31], v[104:107], v[108:111], v[16:31]
	v_mfma_f32_32x32x16_bf16 v[0:15], v[104:107], v[112:115], v[0:15]
	ds_read_b128 v[104:107], v80 offset:32768
	ds_read_b128 v[108:111], v83 offset:49152
	ds_read_b128 v[112:115], v83 offset:53248
	s_waitcnt lgkmcnt(0)
	v_mfma_f32_32x32x16_bf16 v[48:63], v[104:107], v[108:111], v[48:63]
	v_mfma_f32_32x32x16_bf16 v[32:47], v[104:107], v[112:115], v[32:47]
	ds_read_b128 v[104:107], v80 offset:36864
	s_waitcnt lgkmcnt(0)
	v_mfma_f32_32x32x16_bf16 v[16:31], v[104:107], v[108:111], v[16:31]
	v_mfma_f32_32x32x16_bf16 v[0:15], v[104:107], v[112:115], v[0:15]
	ds_read_b128 v[104:107], v82 offset:32768
	ds_read_b128 v[108:111], v85 offset:49152
	ds_read_b128 v[112:115], v85 offset:53248
	s_waitcnt lgkmcnt(0)
	v_mfma_f32_32x32x16_bf16 v[48:63], v[104:107], v[108:111], v[48:63]
	v_mfma_f32_32x32x16_bf16 v[32:47], v[104:107], v[112:115], v[32:47]
	ds_read_b128 v[104:107], v82 offset:36864
	s_waitcnt lgkmcnt(0)
	v_mfma_f32_32x32x16_bf16 v[16:31], v[104:107], v[108:111], v[16:31]
	v_mfma_f32_32x32x16_bf16 v[0:15], v[104:107], v[112:115], v[0:15]
	ds_read_b128 v[104:107], v86 offset:32768
	ds_read_b128 v[108:111], v87 offset:49152
	ds_read_b128 v[112:115], v87 offset:53248
	ds_read_b128 v[144:147], v86 offset:36864
	s_waitcnt vmcnt(0)
	s_waitcnt vmcnt(0) lgkmcnt(0)
	s_barrier
; #define WAIT_V0() asm volatile("s_waitcnt vmcnt(0)" ::: "memory")
; DI void gemm_core(char* smem, int nk, const char* Ab, const char* Bb, const unsigned (&aoff)[4], const unsigned (&boff)[4],
;                   f32x16 (&acc)[2][2]) {
;     ...
;   auto stage = [&](int buf, int kt) __attribute__((always_inline)) {
;     const char* ak = Ab + kt * 128;
;     const char* bk = Bb + kt * 128;
;     char* sa = smem + buf * STAGE_B + w * 4096;
; #pragma unroll
;     for (int i = 0; i < 4; ++i) {
;       __builtin_amdgcn_global_load_lds((const unsigned*)(ak + aoff[i]), (unsigned*)(sa + i * 1024), 16, 0, 0);
;       __builtin_amdgcn_global_load_lds((const unsigned*)(bk + boff[i]), (unsigned*)(sa + 16384 + i * 1024), 16, 0, 0);
;     }
;   };
;   stage(0, 0);
;   WAIT_V0();
;   __syncthreads();
;   for (int kt = 0; kt < nk; ++kt) {
;     const int cur = kt & 1;
;     if (kt + 1 < nk) stage(cur ^ 1, kt + 1);
;     const char* sb = smem + cur * STAGE_B;
; #pragma unroll
;     for (int ks = 0; ks < 4; ++ks) {
;       bf16x8 af[2], bfr[2];
; #pragma unroll
;       for (int mb = 0; mb < 2; ++mb) af[mb] = *(const bf16x8*)(sb + a_base + mb * 4096 + xo[ks]);
; #pragma unroll
;       for (int nb = 0; nb < 2; ++nb) bfr[nb] = *(const bf16x8*)(sb + b_base + nb * 4096 + xo[ks]);
; #pragma unroll
;       for (int mb = 0; mb < 2; ++mb)
; #pragma unroll
;         for (int nb = 0; nb < 2; ++nb)
;           acc[mb][nb] = __builtin_amdgcn_mfma_f32_32x32x16_bf16(af[mb], bfr[nb], acc[mb][nb], 0, 0, 0);
;     }
;     WAIT_V0();
;     __syncthreads();
;   }
	v_mfma_f32_32x32x16_bf16 v[48:63], v[104:107], v[108:111], v[48:63]
	v_mfma_f32_32x32x16_bf16 v[32:47], v[104:107], v[112:115], v[32:47]
	v_mfma_f32_32x32x16_bf16 v[16:31], v[144:147], v[108:111], v[16:31]
	v_mfma_f32_32x32x16_bf16 v[0:15], v[144:147], v[112:115], v[0:15]
	ds_read_b128 v[104:107], v79
	ds_read_b128 v[108:111], v81 offset:16384
	ds_read_b128 v[112:115], v81 offset:20480
	v_lshl_add_u64 v[140:141], v[64:65], 0, s[4:5]
	global_load_lds_dwordx4 v[140:141], off
	s_mov_b32 m0, s19
	v_lshl_add_u64 v[142:143], v[66:67], 0, s[4:5]
	global_load_lds_dwordx4 v76, s[46:47]
	s_mov_b32 m0, s22
	s_nop 0
	global_load_lds_dwordx4 v[142:143], off
	s_mov_b32 m0, s23
	v_lshl_add_u64 v[140:141], v[68:69], 0, s[4:5]
	global_load_lds_dwordx4 v77, s[46:47]
	s_mov_b32 m0, s29
	s_nop 0
	global_load_lds_dwordx4 v[140:141], off
	s_mov_b32 m0, s69
	v_lshl_add_u64 v[142:143], v[70:71], 0, s[4:5]
	global_load_lds_dwordx4 v78, s[46:47]
	s_mov_b32 m0, s70
	s_mov_b64 s[4:5], 0x300
	global_load_lds_dwordx4 v[142:143], off
	s_mov_b32 m0, s71
	s_nop 0
	global_load_lds_dwordx4 v84, s[46:47]
	s_waitcnt lgkmcnt(0)
	v_mfma_f32_32x32x16_bf16 v[48:63], v[104:107], v[108:111], v[48:63]
	s_mov_b32 m0, s84
	v_mfma_f32_32x32x16_bf16 v[32:47], v[104:107], v[112:115], v[32:47]
	ds_read_b128 v[104:107], v79 offset:4096
	s_waitcnt lgkmcnt(0)
	v_mfma_f32_32x32x16_bf16 v[16:31], v[104:107], v[108:111], v[16:31]
	v_mfma_f32_32x32x16_bf16 v[0:15], v[104:107], v[112:115], v[0:15]
	ds_read_b128 v[104:107], v80
	ds_read_b128 v[108:111], v83 offset:16384
	ds_read_b128 v[112:115], v83 offset:20480
	s_waitcnt lgkmcnt(0)
	v_mfma_f32_32x32x16_bf16 v[48:63], v[104:107], v[108:111], v[48:63]
	v_mfma_f32_32x32x16_bf16 v[32:47], v[104:107], v[112:115], v[32:47]
	ds_read_b128 v[104:107], v80 offset:4096
	s_waitcnt lgkmcnt(0)
	v_mfma_f32_32x32x16_bf16 v[16:31], v[104:107], v[108:111], v[16:31]
	v_mfma_f32_32x32x16_bf16 v[0:15], v[104:107], v[112:115], v[0:15]
	ds_read_b128 v[104:107], v82
	ds_read_b128 v[108:111], v85 offset:16384
	ds_read_b128 v[112:115], v85 offset:20480
	s_waitcnt lgkmcnt(0)
	v_mfma_f32_32x32x16_bf16 v[48:63], v[104:107], v[108:111], v[48:63]
	v_mfma_f32_32x32x16_bf16 v[32:47], v[104:107], v[112:115], v[32:47]
	ds_read_b128 v[104:107], v82 offset:4096
	s_waitcnt lgkmcnt(0)
	v_mfma_f32_32x32x16_bf16 v[16:31], v[104:107], v[108:111], v[16:31]
	v_mfma_f32_32x32x16_bf16 v[0:15], v[104:107], v[112:115], v[0:15]
	ds_read_b128 v[104:107], v86
	ds_read_b128 v[108:111], v87 offset:16384
	ds_read_b128 v[112:115], v87 offset:20480
	ds_read_b128 v[144:147], v86 offset:4096
	s_waitcnt vmcnt(0)
	s_waitcnt vmcnt(0) lgkmcnt(0)
	s_barrier
	v_mfma_f32_32x32x16_bf16 v[48:63], v[104:107], v[108:111], v[48:63]
	v_mfma_f32_32x32x16_bf16 v[32:47], v[104:107], v[112:115], v[32:47]
	v_mfma_f32_32x32x16_bf16 v[16:31], v[144:147], v[108:111], v[16:31]
	v_mfma_f32_32x32x16_bf16 v[0:15], v[144:147], v[112:115], v[0:15]
	ds_read_b128 v[104:107], v79 offset:32768
	ds_read_b128 v[108:111], v81 offset:49152
	ds_read_b128 v[112:115], v81 offset:53248
	v_lshl_add_u64 v[140:141], v[64:65], 0, s[4:5]
	global_load_lds_dwordx4 v[140:141], off
	s_mov_b32 m0, s85
	v_lshl_add_u64 v[142:143], v[66:67], 0, s[4:5]
	global_load_lds_dwordx4 v76, s[48:49]
	s_mov_b32 m0, s86
	s_nop 0
	global_load_lds_dwordx4 v[142:143], off
	s_mov_b32 m0, s87
	v_lshl_add_u64 v[140:141], v[68:69], 0, s[4:5]
	global_load_lds_dwordx4 v77, s[48:49]
	s_mov_b32 m0, s88
	s_nop 0
	global_load_lds_dwordx4 v[140:141], off
	s_mov_b32 m0, s89
	v_lshl_add_u64 v[142:143], v[70:71], 0, s[4:5]
	global_load_lds_dwordx4 v78, s[48:49]
	s_mov_b32 m0, s90
	s_mov_b64 s[4:5], 0x380
	global_load_lds_dwordx4 v[142:143], off
	s_mov_b32 m0, s91
	s_nop 0
	global_load_lds_dwordx4 v84, s[48:49]
	s_waitcnt lgkmcnt(0)
	v_mfma_f32_32x32x16_bf16 v[48:63], v[104:107], v[108:111], v[48:63]
	s_mov_b32 m0, s18
	v_mfma_f32_32x32x16_bf16 v[32:47], v[104:107], v[112:115], v[32:47]
	ds_read_b128 v[104:107], v79 offset:36864
	s_waitcnt lgkmcnt(0)
	v_mfma_f32_32x32x16_bf16 v[16:31], v[104:107], v[108:111], v[16:31]
	v_mfma_f32_32x32x16_bf16 v[0:15], v[104:107], v[112:115], v[0:15]
	ds_read_b128 v[104:107], v80 offset:32768
	ds_read_b128 v[108:111], v83 offset:49152
	ds_read_b128 v[112:115], v83 offset:53248
	s_waitcnt lgkmcnt(0)
	v_mfma_f32_32x32x16_bf16 v[48:63], v[104:107], v[108:111], v[48:63]
	v_mfma_f32_32x32x16_bf16 v[32:47], v[104:107], v[112:115], v[32:47]
	ds_read_b128 v[104:107], v80 offset:36864
	s_waitcnt lgkmcnt(0)
	v_mfma_f32_32x32x16_bf16 v[16:31], v[104:107], v[108:111], v[16:31]
	v_mfma_f32_32x32x16_bf16 v[0:15], v[104:107], v[112:115], v[0:15]
	ds_read_b128 v[104:107], v82 offset:32768
	ds_read_b128 v[108:111], v85 offset:49152
	ds_read_b128 v[112:115], v85 offset:53248
	s_waitcnt lgkmcnt(0)
	v_mfma_f32_32x32x16_bf16 v[48:63], v[104:107], v[108:111], v[48:63]
	v_mfma_f32_32x32x16_bf16 v[32:47], v[104:107], v[112:115], v[32:47]
	ds_read_b128 v[104:107], v82 offset:36864
	s_waitcnt lgkmcnt(0)
	v_mfma_f32_32x32x16_bf16 v[16:31], v[104:107], v[108:111], v[16:31]
	v_mfma_f32_32x32x16_bf16 v[0:15], v[104:107], v[112:115], v[0:15]
	ds_read_b128 v[104:107], v86 offset:32768
	ds_read_b128 v[108:111], v87 offset:49152
	ds_read_b128 v[112:115], v87 offset:53248
	ds_read_b128 v[144:147], v86 offset:36864
	s_waitcnt vmcnt(0)
	s_waitcnt vmcnt(0) lgkmcnt(0)
	s_barrier
; #define WAIT_V0() asm volatile("s_waitcnt vmcnt(0)" ::: "memory")
; DI void gemm_core(char* smem, int nk, const char* Ab, const char* Bb, const unsigned (&aoff)[4], const unsigned (&boff)[4],
;                   f32x16 (&acc)[2][2]) {
;     ...
;   auto stage = [&](int buf, int kt) __attribute__((always_inline)) {
;     const char* ak = Ab + kt * 128;
;     const char* bk = Bb + kt * 128;
;     char* sa = smem + buf * STAGE_B + w * 4096;
; #pragma unroll
;     for (int i = 0; i < 4; ++i) {
;       __builtin_amdgcn_global_load_lds((const unsigned*)(ak + aoff[i]), (unsigned*)(sa + i * 1024), 16, 0, 0);
;       __builtin_amdgcn_global_load_lds((const unsigned*)(bk + boff[i]), (unsigned*)(sa + 16384 + i * 1024), 16, 0, 0);
;     }
;   };
;   stage(0, 0);
;   WAIT_V0();
;   __syncthreads();
;   for (int kt = 0; kt < nk; ++kt) {
;     const int cur = kt & 1;
;     if (kt + 1 < nk) stage(cur ^ 1, kt + 1);
;     const char* sb = smem + cur * STAGE_B;
; #pragma unroll
;     for (int ks = 0; ks < 4; ++ks) {
;       bf16x8 af[2], bfr[2];
; #pragma unroll
;       for (int mb = 0; mb < 2; ++mb) af[mb] = *(const bf16x8*)(sb + a_base + mb * 4096 + xo[ks]);
; #pragma unroll
;       for (int nb = 0; nb < 2; ++nb) bfr[nb] = *(const bf16x8*)(sb + b_base + nb * 4096 + xo[ks]);
; #pragma unroll
;       for (int mb = 0; mb < 2; ++mb)
; #pragma unroll
;         for (int nb = 0; nb < 2; ++nb)
;           acc[mb][nb] = __builtin_amdgcn_mfma_f32_32x32x16_bf16(af[mb], bfr[nb], acc[mb][nb], 0, 0, 0);
;     }
;     WAIT_V0();
;     __syncthreads();
;   }
	v_mfma_f32_32x32x16_bf16 v[48:63], v[104:107], v[108:111], v[48:63]
	v_mfma_f32_32x32x16_bf16 v[32:47], v[104:107], v[112:115], v[32:47]
	v_mfma_f32_32x32x16_bf16 v[16:31], v[144:147], v[108:111], v[16:31]
	v_mfma_f32_32x32x16_bf16 v[0:15], v[144:147], v[112:115], v[0:15]
	ds_read_b128 v[104:107], v79
	ds_read_b128 v[108:111], v81 offset:16384
	ds_read_b128 v[112:115], v81 offset:20480
	v_lshl_add_u64 v[140:141], v[64:65], 0, s[4:5]
	global_load_lds_dwordx4 v[140:141], off
	s_mov_b32 m0, s19
	v_lshl_add_u64 v[142:143], v[66:67], 0, s[4:5]
	global_load_lds_dwordx4 v76, s[50:51]
	s_mov_b32 m0, s22
	s_nop 0
	global_load_lds_dwordx4 v[142:143], off
	s_mov_b32 m0, s23
	v_lshl_add_u64 v[140:141], v[68:69], 0, s[4:5]
	global_load_lds_dwordx4 v77, s[50:51]
	s_mov_b32 m0, s29
	s_nop 0
	global_load_lds_dwordx4 v[140:141], off
	s_mov_b32 m0, s69
	v_lshl_add_u64 v[142:143], v[70:71], 0, s[4:5]
	global_load_lds_dwordx4 v78, s[50:51]
	s_mov_b32 m0, s70
	s_mov_b64 s[4:5], 0x400
	global_load_lds_dwordx4 v[142:143], off
	s_mov_b32 m0, s71
	s_nop 0
	global_load_lds_dwordx4 v84, s[50:51]
	s_waitcnt lgkmcnt(0)
	v_mfma_f32_32x32x16_bf16 v[48:63], v[104:107], v[108:111], v[48:63]
	s_mov_b32 m0, s84
	v_readfirstlane_b32 s84, v89
	v_mfma_f32_32x32x16_bf16 v[32:47], v[104:107], v[112:115], v[32:47]
	ds_read_b128 v[104:107], v79 offset:4096
	s_waitcnt lgkmcnt(0)
	v_mfma_f32_32x32x16_bf16 v[16:31], v[104:107], v[108:111], v[16:31]
	v_mfma_f32_32x32x16_bf16 v[0:15], v[104:107], v[112:115], v[0:15]
	ds_read_b128 v[104:107], v80
	ds_read_b128 v[108:111], v83 offset:16384
	ds_read_b128 v[112:115], v83 offset:20480
	s_waitcnt lgkmcnt(0)
	v_mfma_f32_32x32x16_bf16 v[48:63], v[104:107], v[108:111], v[48:63]
	v_mfma_f32_32x32x16_bf16 v[32:47], v[104:107], v[112:115], v[32:47]
	ds_read_b128 v[104:107], v80 offset:4096
	s_waitcnt lgkmcnt(0)
	v_mfma_f32_32x32x16_bf16 v[16:31], v[104:107], v[108:111], v[16:31]
	v_mfma_f32_32x32x16_bf16 v[0:15], v[104:107], v[112:115], v[0:15]
	ds_read_b128 v[104:107], v82
	ds_read_b128 v[108:111], v85 offset:16384
	ds_read_b128 v[112:115], v85 offset:20480
	s_waitcnt lgkmcnt(0)
	v_mfma_f32_32x32x16_bf16 v[48:63], v[104:107], v[108:111], v[48:63]
	v_mfma_f32_32x32x16_bf16 v[32:47], v[104:107], v[112:115], v[32:47]
	ds_read_b128 v[104:107], v82 offset:4096
	s_waitcnt lgkmcnt(0)
	v_mfma_f32_32x32x16_bf16 v[16:31], v[104:107], v[108:111], v[16:31]
	v_mfma_f32_32x32x16_bf16 v[0:15], v[104:107], v[112:115], v[0:15]
	ds_read_b128 v[104:107], v86
	ds_read_b128 v[108:111], v87 offset:16384
	ds_read_b128 v[112:115], v87 offset:20480
	ds_read_b128 v[144:147], v86 offset:4096
	s_waitcnt vmcnt(0)
	s_waitcnt vmcnt(0) lgkmcnt(0)
	s_barrier
	v_mfma_f32_32x32x16_bf16 v[48:63], v[104:107], v[108:111], v[48:63]
	v_mfma_f32_32x32x16_bf16 v[32:47], v[104:107], v[112:115], v[32:47]
	v_mfma_f32_32x32x16_bf16 v[16:31], v[144:147], v[108:111], v[16:31]
	v_mfma_f32_32x32x16_bf16 v[0:15], v[144:147], v[112:115], v[0:15]
	ds_read_b128 v[104:107], v79 offset:32768
	ds_read_b128 v[108:111], v81 offset:49152
	ds_read_b128 v[112:115], v81 offset:53248
	v_lshl_add_u64 v[140:141], v[64:65], 0, s[4:5]
	global_load_lds_dwordx4 v[140:141], off
	s_mov_b32 m0, s85
	v_lshl_add_u64 v[142:143], v[66:67], 0, s[4:5]
	global_load_lds_dwordx4 v76, s[52:53]
	s_mov_b32 m0, s86
	v_readfirstlane_b32 s85, v88
	global_load_lds_dwordx4 v[142:143], off
	s_mov_b32 m0, s87
	v_lshl_add_u64 v[140:141], v[68:69], 0, s[4:5]
	global_load_lds_dwordx4 v77, s[52:53]
	s_mov_b32 m0, s88
	v_readfirstlane_b32 s86, v90
	global_load_lds_dwordx4 v[140:141], off
	s_mov_b32 m0, s89
	v_lshl_add_u64 v[142:143], v[70:71], 0, s[4:5]
	global_load_lds_dwordx4 v78, s[52:53]
	s_mov_b32 m0, s90
	s_mov_b64 s[4:5], 0x480
	global_load_lds_dwordx4 v[142:143], off
	s_mov_b32 m0, s91
	v_readfirstlane_b32 s87, v91
	global_load_lds_dwordx4 v84, s[52:53]
	s_waitcnt lgkmcnt(0)
	v_mfma_f32_32x32x16_bf16 v[48:63], v[104:107], v[108:111], v[48:63]
	s_mov_b32 m0, s18
	v_readfirstlane_b32 s18, v97
	v_readfirstlane_b32 s88, v92
	v_readfirstlane_b32 s89, v93
	v_readfirstlane_b32 s90, v94
	v_readfirstlane_b32 s91, v95
	v_mfma_f32_32x32x16_bf16 v[32:47], v[104:107], v[112:115], v[32:47]
	ds_read_b128 v[104:107], v79 offset:36864
	s_waitcnt lgkmcnt(0)
	v_mfma_f32_32x32x16_bf16 v[16:31], v[104:107], v[108:111], v[16:31]
	v_mfma_f32_32x32x16_bf16 v[0:15], v[104:107], v[112:115], v[0:15]
	ds_read_b128 v[104:107], v80 offset:32768
	ds_read_b128 v[108:111], v83 offset:49152
	ds_read_b128 v[112:115], v83 offset:53248
	s_waitcnt lgkmcnt(0)
	v_mfma_f32_32x32x16_bf16 v[48:63], v[104:107], v[108:111], v[48:63]
	v_mfma_f32_32x32x16_bf16 v[32:47], v[104:107], v[112:115], v[32:47]
	ds_read_b128 v[104:107], v80 offset:36864
	s_waitcnt lgkmcnt(0)
	v_mfma_f32_32x32x16_bf16 v[16:31], v[104:107], v[108:111], v[16:31]
	v_mfma_f32_32x32x16_bf16 v[0:15], v[104:107], v[112:115], v[0:15]
	ds_read_b128 v[104:107], v82 offset:32768
	ds_read_b128 v[108:111], v85 offset:49152
	ds_read_b128 v[112:115], v85 offset:53248
	s_waitcnt lgkmcnt(0)
	v_mfma_f32_32x32x16_bf16 v[48:63], v[104:107], v[108:111], v[48:63]
	v_mfma_f32_32x32x16_bf16 v[32:47], v[104:107], v[112:115], v[32:47]
	ds_read_b128 v[104:107], v82 offset:36864
	s_waitcnt lgkmcnt(0)
	v_mfma_f32_32x32x16_bf16 v[16:31], v[104:107], v[108:111], v[16:31]
	v_mfma_f32_32x32x16_bf16 v[0:15], v[104:107], v[112:115], v[0:15]
	ds_read_b128 v[104:107], v86 offset:32768
	ds_read_b128 v[108:111], v87 offset:49152
	ds_read_b128 v[112:115], v87 offset:53248
	ds_read_b128 v[144:147], v86 offset:36864
	s_waitcnt vmcnt(0)
	s_waitcnt vmcnt(0) lgkmcnt(0)
	s_barrier
; #define WAIT_V0() asm volatile("s_waitcnt vmcnt(0)" ::: "memory")
; DI void gemm_core(char* smem, int nk, const char* Ab, const char* Bb, const unsigned (&aoff)[4], const unsigned (&boff)[4],
;                   f32x16 (&acc)[2][2]) {
;     ...
;   auto stage = [&](int buf, int kt) __attribute__((always_inline)) {
;     const char* ak = Ab + kt * 128;
;     const char* bk = Bb + kt * 128;
;     char* sa = smem + buf * STAGE_B + w * 4096;
; #pragma unroll
;     for (int i = 0; i < 4; ++i) {
;       __builtin_amdgcn_global_load_lds((const unsigned*)(ak + aoff[i]), (unsigned*)(sa + i * 1024), 16, 0, 0);
;       __builtin_amdgcn_global_load_lds((const unsigned*)(bk + boff[i]), (unsigned*)(sa + 16384 + i * 1024), 16, 0, 0);
;     }
;   };
;   stage(0, 0);
;   WAIT_V0();
;   __syncthreads();
;   for (int kt = 0; kt < nk; ++kt) {
;     const int cur = kt & 1;
;     if (kt + 1 < nk) stage(cur ^ 1, kt + 1);
;     const char* sb = smem + cur * STAGE_B;
; #pragma unroll
;     for (int ks = 0; ks < 4; ++ks) {
;       bf16x8 af[2], bfr[2];
; #pragma unroll
;       for (int mb = 0; mb < 2; ++mb) af[mb] = *(const bf16x8*)(sb + a_base + mb * 4096 + xo[ks]);
; #pragma unroll
;       for (int nb = 0; nb < 2; ++nb) bfr[nb] = *(const bf16x8*)(sb + b_base + nb * 4096 + xo[ks]);
; #pragma unroll
;       for (int mb = 0; mb < 2; ++mb)
; #pragma unroll
;         for (int nb = 0; nb < 2; ++nb)
;           acc[mb][nb] = __builtin_amdgcn_mfma_f32_32x32x16_bf16(af[mb], bfr[nb], acc[mb][nb], 0, 0, 0);
;     }
;     WAIT_V0();
;     __syncthreads();
;   }
	v_mfma_f32_32x32x16_bf16 v[48:63], v[104:107], v[108:111], v[48:63]
	v_mfma_f32_32x32x16_bf16 v[32:47], v[104:107], v[112:115], v[32:47]
	v_mfma_f32_32x32x16_bf16 v[16:31], v[144:147], v[108:111], v[16:31]
	v_mfma_f32_32x32x16_bf16 v[0:15], v[144:147], v[112:115], v[0:15]
	v_lshl_add_u64 v[104:105], v[64:65], 0, s[4:5]
	global_load_lds_dwordx4 v[104:105], off
	s_mov_b32 m0, s19
	v_lshl_add_u64 v[104:105], v[66:67], 0, s[4:5]
	global_load_lds_dwordx4 v76, s[54:55]
	s_mov_b32 m0, s22
	v_readfirstlane_b32 s19, v96
	global_load_lds_dwordx4 v[104:105], off
	s_mov_b32 m0, s23
	v_lshl_add_u64 v[104:105], v[68:69], 0, s[4:5]
	global_load_lds_dwordx4 v77, s[54:55]
	s_mov_b32 m0, s29
	v_readfirstlane_b32 s22, v98
	global_load_lds_dwordx4 v[104:105], off
	s_mov_b32 m0, s69
	v_lshl_add_u64 v[104:105], v[70:71], 0, s[4:5]
	global_load_lds_dwordx4 v78, s[54:55]
	s_mov_b32 m0, s70
	s_mov_b64 s[4:5], 0x500
	global_load_lds_dwordx4 v[104:105], off
	s_mov_b32 m0, s71
	v_lshl_add_u64 v[96:97], v[66:67], 0, s[4:5]
	global_load_lds_dwordx4 v84, s[54:55]
	ds_read_b128 v[104:107], v79
	ds_read_b128 v[108:111], v81 offset:16384
	ds_read_b128 v[112:115], v81 offset:20480
	s_waitcnt lgkmcnt(0)
	v_mfma_f32_32x32x16_bf16 v[48:63], v[104:107], v[108:111], v[48:63]
	s_mov_b32 m0, s18
	v_readfirstlane_b32 s23, v99
	v_readfirstlane_b32 s29, v100
	v_readfirstlane_b32 s69, v101
	v_readfirstlane_b32 s70, v102
	v_readfirstlane_b32 s71, v103
	v_mfma_f32_32x32x16_bf16 v[32:47], v[104:107], v[112:115], v[32:47]
	ds_read_b128 v[104:107], v79 offset:4096
	s_waitcnt lgkmcnt(0)
	v_mfma_f32_32x32x16_bf16 v[16:31], v[104:107], v[108:111], v[16:31]
	v_mfma_f32_32x32x16_bf16 v[0:15], v[104:107], v[112:115], v[0:15]
	ds_read_b128 v[104:107], v80
	ds_read_b128 v[108:111], v83 offset:16384
	ds_read_b128 v[112:115], v83 offset:20480
	s_waitcnt lgkmcnt(0)
	v_mfma_f32_32x32x16_bf16 v[48:63], v[104:107], v[108:111], v[48:63]
	v_mfma_f32_32x32x16_bf16 v[32:47], v[104:107], v[112:115], v[32:47]
	ds_read_b128 v[104:107], v80 offset:4096
	s_waitcnt lgkmcnt(0)
	v_mfma_f32_32x32x16_bf16 v[16:31], v[104:107], v[108:111], v[16:31]
	v_mfma_f32_32x32x16_bf16 v[0:15], v[104:107], v[112:115], v[0:15]
	ds_read_b128 v[104:107], v82
	ds_read_b128 v[108:111], v85 offset:16384
	ds_read_b128 v[112:115], v85 offset:20480
	s_waitcnt lgkmcnt(0)
	v_mfma_f32_32x32x16_bf16 v[48:63], v[104:107], v[108:111], v[48:63]
	v_mfma_f32_32x32x16_bf16 v[32:47], v[104:107], v[112:115], v[32:47]
	ds_read_b128 v[104:107], v82 offset:4096
	s_waitcnt lgkmcnt(0)
	v_mfma_f32_32x32x16_bf16 v[16:31], v[104:107], v[108:111], v[16:31]
	v_mfma_f32_32x32x16_bf16 v[0:15], v[104:107], v[112:115], v[0:15]
	ds_read_b128 v[104:107], v86
	ds_read_b128 v[108:111], v87 offset:16384
	ds_read_b128 v[112:115], v87 offset:20480
	ds_read_b128 v[144:147], v86 offset:4096
	s_waitcnt vmcnt(0)
	s_waitcnt vmcnt(0) lgkmcnt(0)
	s_barrier
	v_mfma_f32_32x32x16_bf16 v[48:63], v[104:107], v[108:111], v[48:63]
	v_mfma_f32_32x32x16_bf16 v[32:47], v[104:107], v[112:115], v[32:47]
	v_mfma_f32_32x32x16_bf16 v[16:31], v[144:147], v[108:111], v[16:31]
	v_mfma_f32_32x32x16_bf16 v[0:15], v[144:147], v[112:115], v[0:15]
	v_lshl_add_u64 v[104:105], v[64:65], 0, s[4:5]
	global_load_lds_dwordx4 v[104:105], off
	s_mov_b32 m0, s19
	s_nop 0
	global_load_lds_dwordx4 v76, s[56:57]
	s_mov_b32 m0, s22
	s_nop 0
	global_load_lds_dwordx4 v[96:97], off
	s_mov_b32 m0, s23
	v_lshl_add_u64 v[96:97], v[68:69], 0, s[4:5]
	global_load_lds_dwordx4 v77, s[56:57]
	s_mov_b32 m0, s29
	s_nop 0
	global_load_lds_dwordx4 v[96:97], off
	s_mov_b32 m0, s69
	v_lshl_add_u64 v[96:97], v[70:71], 0, s[4:5]
	global_load_lds_dwordx4 v78, s[56:57]
	s_mov_b32 m0, s70
	s_mov_b64 s[4:5], 0x580
	global_load_lds_dwordx4 v[96:97], off
	s_mov_b32 m0, s71
	v_lshl_add_u64 v[88:89], v[66:67], 0, s[4:5]
	global_load_lds_dwordx4 v84, s[56:57]
	ds_read_b128 v[96:99], v79 offset:32768
	ds_read_b128 v[100:103], v81 offset:49152
	ds_read_b128 v[104:107], v81 offset:53248
	s_waitcnt lgkmcnt(0)
	v_mfma_f32_32x32x16_bf16 v[48:63], v[96:99], v[100:103], v[48:63]
	s_mov_b32 m0, s84
	v_mfma_f32_32x32x16_bf16 v[32:47], v[96:99], v[104:107], v[32:47]
	ds_read_b128 v[96:99], v79 offset:36864
	s_waitcnt lgkmcnt(0)
	v_mfma_f32_32x32x16_bf16 v[16:31], v[96:99], v[100:103], v[16:31]
	v_mfma_f32_32x32x16_bf16 v[0:15], v[96:99], v[104:107], v[0:15]
	ds_read_b128 v[96:99], v80 offset:32768
	ds_read_b128 v[100:103], v83 offset:49152
	ds_read_b128 v[104:107], v83 offset:53248
	s_waitcnt lgkmcnt(0)
	v_mfma_f32_32x32x16_bf16 v[48:63], v[96:99], v[100:103], v[48:63]
	v_mfma_f32_32x32x16_bf16 v[32:47], v[96:99], v[104:107], v[32:47]
	ds_read_b128 v[96:99], v80 offset:36864
	s_waitcnt lgkmcnt(0)
	v_mfma_f32_32x32x16_bf16 v[16:31], v[96:99], v[100:103], v[16:31]
	v_mfma_f32_32x32x16_bf16 v[0:15], v[96:99], v[104:107], v[0:15]
	ds_read_b128 v[96:99], v82 offset:32768
	ds_read_b128 v[100:103], v85 offset:49152
	ds_read_b128 v[104:107], v85 offset:53248
	s_waitcnt lgkmcnt(0)
	v_mfma_f32_32x32x16_bf16 v[48:63], v[96:99], v[100:103], v[48:63]
	v_mfma_f32_32x32x16_bf16 v[32:47], v[96:99], v[104:107], v[32:47]
	ds_read_b128 v[96:99], v82 offset:36864
	s_waitcnt lgkmcnt(0)
	v_mfma_f32_32x32x16_bf16 v[16:31], v[96:99], v[100:103], v[16:31]
	v_mfma_f32_32x32x16_bf16 v[0:15], v[96:99], v[104:107], v[0:15]
	ds_read_b128 v[96:99], v86 offset:32768
	ds_read_b128 v[100:103], v87 offset:49152
	ds_read_b128 v[104:107], v87 offset:53248
	ds_read_b128 v[144:147], v86 offset:36864
	s_waitcnt vmcnt(0)
	s_waitcnt vmcnt(0) lgkmcnt(0)
	s_barrier
; #define WAIT_V0() asm volatile("s_waitcnt vmcnt(0)" ::: "memory")
; DI void gemm_core(char* smem, int nk, const char* Ab, const char* Bb, const unsigned (&aoff)[4], const unsigned (&boff)[4],
;                   f32x16 (&acc)[2][2]) {
;     ...
;   auto stage = [&](int buf, int kt) __attribute__((always_inline)) {
;     const char* ak = Ab + kt * 128;
;     const char* bk = Bb + kt * 128;
;     char* sa = smem + buf * STAGE_B + w * 4096;
; #pragma unroll
;     for (int i = 0; i < 4; ++i) {
;       __builtin_amdgcn_global_load_lds((const unsigned*)(ak + aoff[i]), (unsigned*)(sa + i * 1024), 16, 0, 0);
;       __builtin_amdgcn_global_load_lds((const unsigned*)(bk + boff[i]), (unsigned*)(sa + 16384 + i * 1024), 16, 0, 0);
;     }
;   };
;   stage(0, 0);
;   WAIT_V0();
;   __syncthreads();
;   for (int kt = 0; kt < nk; ++kt) {
;     const int cur = kt & 1;
;     if (kt + 1 < nk) stage(cur ^ 1, kt + 1);
;     const char* sb = smem + cur * STAGE_B;
; #pragma unroll
;     for (int ks = 0; ks < 4; ++ks) {
;       bf16x8 af[2], bfr[2];
; #pragma unroll
;       for (int mb = 0; mb < 2; ++mb) af[mb] = *(const bf16x8*)(sb + a_base + mb * 4096 + xo[ks]);
; #pragma unroll
;       for (int nb = 0; nb < 2; ++nb) bfr[nb] = *(const bf16x8*)(sb + b_base + nb * 4096 + xo[ks]);
; #pragma unroll
;       for (int mb = 0; mb < 2; ++mb)
; #pragma unroll
;         for (int nb = 0; nb < 2; ++nb)
;           acc[mb][nb] = __builtin_amdgcn_mfma_f32_32x32x16_bf16(af[mb], bfr[nb], acc[mb][nb], 0, 0, 0);
;     }
;     WAIT_V0();
;     __syncthreads();
;   }
	v_mfma_f32_32x32x16_bf16 v[48:63], v[96:99], v[100:103], v[48:63]
	v_mfma_f32_32x32x16_bf16 v[32:47], v[96:99], v[104:107], v[32:47]
	v_mfma_f32_32x32x16_bf16 v[16:31], v[144:147], v[100:103], v[16:31]
	v_mfma_f32_32x32x16_bf16 v[0:15], v[144:147], v[104:107], v[0:15]
	v_lshl_add_u64 v[96:97], v[64:65], 0, s[4:5]
	global_load_lds_dwordx4 v[96:97], off
	s_mov_b32 m0, s85
	s_nop 0
	global_load_lds_dwordx4 v76, s[58:59]
	s_mov_b32 m0, s86
	s_nop 0
	global_load_lds_dwordx4 v[88:89], off
	s_mov_b32 m0, s87
	v_lshl_add_u64 v[88:89], v[68:69], 0, s[4:5]
	global_load_lds_dwordx4 v77, s[58:59]
	s_mov_b32 m0, s88
	s_nop 0
	global_load_lds_dwordx4 v[88:89], off
	s_mov_b32 m0, s89
	v_lshl_add_u64 v[88:89], v[70:71], 0, s[4:5]
	global_load_lds_dwordx4 v78, s[58:59]
	s_mov_b32 m0, s90
	s_mov_b64 s[4:5], 0x600
	global_load_lds_dwordx4 v[88:89], off
	s_mov_b32 m0, s91
	s_nop 0
	global_load_lds_dwordx4 v84, s[58:59]
	ds_read_b128 v[88:91], v79
	ds_read_b128 v[92:95], v81 offset:16384
	ds_read_b128 v[96:99], v81 offset:20480
	s_waitcnt lgkmcnt(0)
	v_mfma_f32_32x32x16_bf16 v[48:63], v[88:91], v[92:95], v[48:63]
	s_mov_b32 m0, s18
	v_mfma_f32_32x32x16_bf16 v[32:47], v[88:91], v[96:99], v[32:47]
	ds_read_b128 v[88:91], v79 offset:4096
	s_waitcnt lgkmcnt(0)
	v_mfma_f32_32x32x16_bf16 v[16:31], v[88:91], v[92:95], v[16:31]
	v_mfma_f32_32x32x16_bf16 v[0:15], v[88:91], v[96:99], v[0:15]
	ds_read_b128 v[88:91], v80
	ds_read_b128 v[92:95], v83 offset:16384
	ds_read_b128 v[96:99], v83 offset:20480
	s_waitcnt lgkmcnt(0)
	v_mfma_f32_32x32x16_bf16 v[48:63], v[88:91], v[92:95], v[48:63]
	v_mfma_f32_32x32x16_bf16 v[32:47], v[88:91], v[96:99], v[32:47]
	ds_read_b128 v[88:91], v80 offset:4096
	s_waitcnt lgkmcnt(0)
	v_mfma_f32_32x32x16_bf16 v[16:31], v[88:91], v[92:95], v[16:31]
	v_mfma_f32_32x32x16_bf16 v[0:15], v[88:91], v[96:99], v[0:15]
	ds_read_b128 v[88:91], v82
	ds_read_b128 v[92:95], v85 offset:16384
	ds_read_b128 v[96:99], v85 offset:20480
	s_waitcnt lgkmcnt(0)
	v_mfma_f32_32x32x16_bf16 v[48:63], v[88:91], v[92:95], v[48:63]
	v_mfma_f32_32x32x16_bf16 v[32:47], v[88:91], v[96:99], v[32:47]
	ds_read_b128 v[88:91], v82 offset:4096
	s_waitcnt lgkmcnt(0)
	v_mfma_f32_32x32x16_bf16 v[16:31], v[88:91], v[92:95], v[16:31]
	v_mfma_f32_32x32x16_bf16 v[0:15], v[88:91], v[96:99], v[0:15]
	ds_read_b128 v[88:91], v86
	ds_read_b128 v[92:95], v87 offset:16384
	ds_read_b128 v[96:99], v87 offset:20480
	ds_read_b128 v[144:147], v86 offset:4096
	s_waitcnt vmcnt(0)
	s_waitcnt vmcnt(0) lgkmcnt(0)
	s_barrier
	v_mfma_f32_32x32x16_bf16 v[48:63], v[88:91], v[92:95], v[48:63]
	v_mfma_f32_32x32x16_bf16 v[32:47], v[88:91], v[96:99], v[32:47]
	v_mfma_f32_32x32x16_bf16 v[16:31], v[144:147], v[92:95], v[16:31]
	v_mfma_f32_32x32x16_bf16 v[0:15], v[144:147], v[96:99], v[0:15]
	ds_read_b128 v[88:91], v79 offset:32768
	ds_read_b128 v[92:95], v81 offset:49152
	ds_read_b128 v[96:99], v81 offset:53248
	v_lshl_add_u64 v[140:141], v[64:65], 0, s[4:5]
	global_load_lds_dwordx4 v[140:141], off
	s_mov_b32 m0, s19
	v_lshl_add_u64 v[142:143], v[66:67], 0, s[4:5]
	global_load_lds_dwordx4 v76, s[60:61]
	s_mov_b32 m0, s22
	s_nop 0
	global_load_lds_dwordx4 v[142:143], off
	s_mov_b32 m0, s23
	v_lshl_add_u64 v[140:141], v[68:69], 0, s[4:5]
	global_load_lds_dwordx4 v77, s[60:61]
	s_mov_b32 m0, s29
	s_nop 0
	global_load_lds_dwordx4 v[140:141], off
	s_mov_b32 m0, s69
	v_lshl_add_u64 v[142:143], v[70:71], 0, s[4:5]
	global_load_lds_dwordx4 v78, s[60:61]
	s_mov_b32 m0, s70
	s_mov_b64 s[4:5], 0x680
	global_load_lds_dwordx4 v[142:143], off
	s_mov_b32 m0, s71
	s_nop 0
	global_load_lds_dwordx4 v84, s[60:61]
	s_waitcnt lgkmcnt(0)
	v_mfma_f32_32x32x16_bf16 v[48:63], v[88:91], v[92:95], v[48:63]
	s_mov_b32 m0, s84
	v_mfma_f32_32x32x16_bf16 v[32:47], v[88:91], v[96:99], v[32:47]
	ds_read_b128 v[88:91], v79 offset:36864
	s_waitcnt lgkmcnt(0)
	v_mfma_f32_32x32x16_bf16 v[16:31], v[88:91], v[92:95], v[16:31]
	v_mfma_f32_32x32x16_bf16 v[0:15], v[88:91], v[96:99], v[0:15]
	ds_read_b128 v[88:91], v80 offset:32768
	ds_read_b128 v[92:95], v83 offset:49152
	ds_read_b128 v[96:99], v83 offset:53248
	s_waitcnt lgkmcnt(0)
	v_mfma_f32_32x32x16_bf16 v[48:63], v[88:91], v[92:95], v[48:63]
	v_mfma_f32_32x32x16_bf16 v[32:47], v[88:91], v[96:99], v[32:47]
	ds_read_b128 v[88:91], v80 offset:36864
	s_waitcnt lgkmcnt(0)
	v_mfma_f32_32x32x16_bf16 v[16:31], v[88:91], v[92:95], v[16:31]
	v_mfma_f32_32x32x16_bf16 v[0:15], v[88:91], v[96:99], v[0:15]
	ds_read_b128 v[88:91], v82 offset:32768
	ds_read_b128 v[92:95], v85 offset:49152
	ds_read_b128 v[96:99], v85 offset:53248
	s_waitcnt lgkmcnt(0)
	v_mfma_f32_32x32x16_bf16 v[48:63], v[88:91], v[92:95], v[48:63]
	v_mfma_f32_32x32x16_bf16 v[32:47], v[88:91], v[96:99], v[32:47]
	ds_read_b128 v[88:91], v82 offset:36864
	s_waitcnt lgkmcnt(0)
	v_mfma_f32_32x32x16_bf16 v[16:31], v[88:91], v[92:95], v[16:31]
	v_mfma_f32_32x32x16_bf16 v[0:15], v[88:91], v[96:99], v[0:15]
	ds_read_b128 v[88:91], v86 offset:32768
	ds_read_b128 v[92:95], v87 offset:49152
	ds_read_b128 v[96:99], v87 offset:53248
	ds_read_b128 v[144:147], v86 offset:36864
	s_waitcnt vmcnt(0)
	s_waitcnt vmcnt(0) lgkmcnt(0)
	s_barrier
; #define WAIT_V0() asm volatile("s_waitcnt vmcnt(0)" ::: "memory")
; DI void gemm_core(char* smem, int nk, const char* Ab, const char* Bb, const unsigned (&aoff)[4], const unsigned (&boff)[4],
;                   f32x16 (&acc)[2][2]) {
;     ...
;   auto stage = [&](int buf, int kt) __attribute__((always_inline)) {
;     const char* ak = Ab + kt * 128;
;     const char* bk = Bb + kt * 128;
;     char* sa = smem + buf * STAGE_B + w * 4096;
; #pragma unroll
;     for (int i = 0; i < 4; ++i) {
;       __builtin_amdgcn_global_load_lds((const unsigned*)(ak + aoff[i]), (unsigned*)(sa + i * 1024), 16, 0, 0);
;       __builtin_amdgcn_global_load_lds((const unsigned*)(bk + boff[i]), (unsigned*)(sa + 16384 + i * 1024), 16, 0, 0);
;     }
;   };
;   stage(0, 0);
;   WAIT_V0();
;   __syncthreads();
;   for (int kt = 0; kt < nk; ++kt) {
;     const int cur = kt & 1;
;     if (kt + 1 < nk) stage(cur ^ 1, kt + 1);
;     const char* sb = smem + cur * STAGE_B;
; #pragma unroll
;     for (int ks = 0; ks < 4; ++ks) {
;       bf16x8 af[2], bfr[2];
; #pragma unroll
;       for (int mb = 0; mb < 2; ++mb) af[mb] = *(const bf16x8*)(sb + a_base + mb * 4096 + xo[ks]);
; #pragma unroll
;       for (int nb = 0; nb < 2; ++nb) bfr[nb] = *(const bf16x8*)(sb + b_base + nb * 4096 + xo[ks]);
; #pragma unroll
;       for (int mb = 0; mb < 2; ++mb)
; #pragma unroll
;         for (int nb = 0; nb < 2; ++nb)
;           acc[mb][nb] = __builtin_amdgcn_mfma_f32_32x32x16_bf16(af[mb], bfr[nb], acc[mb][nb], 0, 0, 0);
;     }
;     WAIT_V0();
;     __syncthreads();
;   }
	v_mfma_f32_32x32x16_bf16 v[48:63], v[88:91], v[92:95], v[48:63]
	v_mfma_f32_32x32x16_bf16 v[32:47], v[88:91], v[96:99], v[32:47]
	v_mfma_f32_32x32x16_bf16 v[16:31], v[144:147], v[92:95], v[16:31]
	v_mfma_f32_32x32x16_bf16 v[0:15], v[144:147], v[96:99], v[0:15]
	ds_read_b128 v[88:91], v79
	ds_read_b128 v[92:95], v81 offset:16384
	ds_read_b128 v[96:99], v81 offset:20480
	v_lshl_add_u64 v[140:141], v[64:65], 0, s[4:5]
	global_load_lds_dwordx4 v[140:141], off
	s_mov_b32 m0, s85
	v_lshl_add_u64 v[142:143], v[66:67], 0, s[4:5]
	global_load_lds_dwordx4 v76, s[62:63]
	s_mov_b32 m0, s86
	s_nop 0
	global_load_lds_dwordx4 v[142:143], off
	s_mov_b32 m0, s87
	v_lshl_add_u64 v[140:141], v[68:69], 0, s[4:5]
	global_load_lds_dwordx4 v77, s[62:63]
	s_mov_b32 m0, s88
	s_nop 0
	global_load_lds_dwordx4 v[140:141], off
	s_mov_b32 m0, s89
	v_lshl_add_u64 v[142:143], v[70:71], 0, s[4:5]
	global_load_lds_dwordx4 v78, s[62:63]
	s_mov_b32 m0, s90
	s_mov_b64 s[4:5], 0x700
	global_load_lds_dwordx4 v[142:143], off
	s_mov_b32 m0, s91
	s_nop 0
	global_load_lds_dwordx4 v84, s[62:63]
	s_waitcnt lgkmcnt(0)
	v_mfma_f32_32x32x16_bf16 v[48:63], v[88:91], v[92:95], v[48:63]
	s_mov_b32 m0, s18
	v_mfma_f32_32x32x16_bf16 v[32:47], v[88:91], v[96:99], v[32:47]
	ds_read_b128 v[88:91], v79 offset:4096
	s_waitcnt lgkmcnt(0)
	v_mfma_f32_32x32x16_bf16 v[16:31], v[88:91], v[92:95], v[16:31]
	v_mfma_f32_32x32x16_bf16 v[0:15], v[88:91], v[96:99], v[0:15]
	ds_read_b128 v[88:91], v80
	ds_read_b128 v[92:95], v83 offset:16384
	ds_read_b128 v[96:99], v83 offset:20480
	s_waitcnt lgkmcnt(0)
	v_mfma_f32_32x32x16_bf16 v[48:63], v[88:91], v[92:95], v[48:63]
	v_mfma_f32_32x32x16_bf16 v[32:47], v[88:91], v[96:99], v[32:47]
	ds_read_b128 v[88:91], v80 offset:4096
	s_waitcnt lgkmcnt(0)
	v_mfma_f32_32x32x16_bf16 v[16:31], v[88:91], v[92:95], v[16:31]
	v_mfma_f32_32x32x16_bf16 v[0:15], v[88:91], v[96:99], v[0:15]
	ds_read_b128 v[88:91], v82
	ds_read_b128 v[92:95], v85 offset:16384
	ds_read_b128 v[96:99], v85 offset:20480
	s_waitcnt lgkmcnt(0)
	v_mfma_f32_32x32x16_bf16 v[48:63], v[88:91], v[92:95], v[48:63]
	v_mfma_f32_32x32x16_bf16 v[32:47], v[88:91], v[96:99], v[32:47]
	ds_read_b128 v[88:91], v82 offset:4096
	s_waitcnt lgkmcnt(0)
	v_mfma_f32_32x32x16_bf16 v[16:31], v[88:91], v[92:95], v[16:31]
	v_mfma_f32_32x32x16_bf16 v[0:15], v[88:91], v[96:99], v[0:15]
	ds_read_b128 v[88:91], v86
	ds_read_b128 v[92:95], v87 offset:16384
	ds_read_b128 v[96:99], v87 offset:20480
	ds_read_b128 v[144:147], v86 offset:4096
	s_waitcnt vmcnt(0)
	s_waitcnt vmcnt(0) lgkmcnt(0)
	s_barrier
	v_mfma_f32_32x32x16_bf16 v[48:63], v[88:91], v[92:95], v[48:63]
	v_mfma_f32_32x32x16_bf16 v[32:47], v[88:91], v[96:99], v[32:47]
	v_mfma_f32_32x32x16_bf16 v[16:31], v[144:147], v[92:95], v[16:31]
	v_mfma_f32_32x32x16_bf16 v[0:15], v[144:147], v[96:99], v[0:15]
	v_lshl_add_u64 v[88:89], v[64:65], 0, s[4:5]
	global_load_lds_dwordx4 v[88:89], off
	s_mov_b32 m0, s19
	v_lshl_add_u64 v[88:89], v[66:67], 0, s[4:5]
	global_load_lds_dwordx4 v76, s[64:65]
	s_mov_b32 m0, s22
	s_nop 0
	global_load_lds_dwordx4 v[88:89], off
	s_mov_b32 m0, s23
	v_lshl_add_u64 v[88:89], v[68:69], 0, s[4:5]
	global_load_lds_dwordx4 v77, s[64:65]
	s_mov_b32 m0, s29
	s_nop 0
	global_load_lds_dwordx4 v[88:89], off
	s_mov_b32 m0, s69
	v_lshl_add_u64 v[88:89], v[70:71], 0, s[4:5]
	global_load_lds_dwordx4 v78, s[64:65]
	s_mov_b32 m0, s70
	s_mov_b64 s[4:5], 0x780
	global_load_lds_dwordx4 v[88:89], off
	s_mov_b32 m0, s71
	v_lshl_add_u64 v[64:65], v[64:65], 0, s[4:5]
	global_load_lds_dwordx4 v84, s[64:65]
	ds_read_b128 v[88:91], v79 offset:32768
	ds_read_b128 v[92:95], v81 offset:49152
	ds_read_b128 v[96:99], v81 offset:53248
	s_waitcnt lgkmcnt(0)
	v_mfma_f32_32x32x16_bf16 v[48:63], v[88:91], v[92:95], v[48:63]
	s_mov_b32 m0, s84
	s_movk_i32 s4, 0x4000
	v_mfma_f32_32x32x16_bf16 v[32:47], v[88:91], v[96:99], v[32:47]
	ds_read_b128 v[88:91], v79 offset:36864
	s_waitcnt lgkmcnt(0)
	v_mfma_f32_32x32x16_bf16 v[16:31], v[88:91], v[92:95], v[16:31]
	v_mfma_f32_32x32x16_bf16 v[0:15], v[88:91], v[96:99], v[0:15]
	ds_read_b128 v[88:91], v80 offset:32768
	ds_read_b128 v[92:95], v83 offset:49152
	ds_read_b128 v[96:99], v83 offset:53248
	s_waitcnt lgkmcnt(0)
	v_mfma_f32_32x32x16_bf16 v[48:63], v[88:91], v[92:95], v[48:63]
	v_mfma_f32_32x32x16_bf16 v[32:47], v[88:91], v[96:99], v[32:47]
	ds_read_b128 v[88:91], v80 offset:36864
	s_waitcnt lgkmcnt(0)
	v_mfma_f32_32x32x16_bf16 v[16:31], v[88:91], v[92:95], v[16:31]
	v_mfma_f32_32x32x16_bf16 v[0:15], v[88:91], v[96:99], v[0:15]
	ds_read_b128 v[88:91], v82 offset:32768
	ds_read_b128 v[92:95], v85 offset:49152
	ds_read_b128 v[96:99], v85 offset:53248
	s_waitcnt lgkmcnt(0)
	v_mfma_f32_32x32x16_bf16 v[48:63], v[88:91], v[92:95], v[48:63]
	v_mfma_f32_32x32x16_bf16 v[32:47], v[88:91], v[96:99], v[32:47]
	ds_read_b128 v[88:91], v82 offset:36864
	s_waitcnt lgkmcnt(0)
	v_mfma_f32_32x32x16_bf16 v[16:31], v[88:91], v[92:95], v[16:31]
	v_mfma_f32_32x32x16_bf16 v[0:15], v[88:91], v[96:99], v[0:15]
	ds_read_b128 v[88:91], v86 offset:32768
	ds_read_b128 v[92:95], v87 offset:49152
	ds_read_b128 v[96:99], v87 offset:53248
	s_waitcnt lgkmcnt(0)
	v_mfma_f32_32x32x16_bf16 v[48:63], v[88:91], v[92:95], v[48:63]
	v_mfma_f32_32x32x16_bf16 v[32:47], v[88:91], v[96:99], v[32:47]
	ds_read_b128 v[88:91], v86 offset:36864
	s_waitcnt vmcnt(0)
	s_waitcnt vmcnt(0) lgkmcnt(0)
	s_barrier
; #define WAIT_V0() asm volatile("s_waitcnt vmcnt(0)" ::: "memory")
; DI void gemm_core(char* smem, int nk, const char* Ab, const char* Bb, const unsigned (&aoff)[4], const unsigned (&boff)[4],
;                   f32x16 (&acc)[2][2]) {
;     ...
;   auto stage = [&](int buf, int kt) __attribute__((always_inline)) {
;     const char* ak = Ab + kt * 128;
;     const char* bk = Bb + kt * 128;
;     char* sa = smem + buf * STAGE_B + w * 4096;
; #pragma unroll
;     for (int i = 0; i < 4; ++i) {
;       __builtin_amdgcn_global_load_lds((const unsigned*)(ak + aoff[i]), (unsigned*)(sa + i * 1024), 16, 0, 0);
;       __builtin_amdgcn_global_load_lds((const unsigned*)(bk + boff[i]), (unsigned*)(sa + 16384 + i * 1024), 16, 0, 0);
;     }
;   };
;   stage(0, 0);
;   WAIT_V0();
;   __syncthreads();
;   for (int kt = 0; kt < nk; ++kt) {
;     const int cur = kt & 1;
;     if (kt + 1 < nk) stage(cur ^ 1, kt + 1);
;     const char* sb = smem + cur * STAGE_B;
; #pragma unroll
;     for (int ks = 0; ks < 4; ++ks) {
;       bf16x8 af[2], bfr[2];
; #pragma unroll
;       for (int mb = 0; mb < 2; ++mb) af[mb] = *(const bf16x8*)(sb + a_base + mb * 4096 + xo[ks]);
; #pragma unroll
;       for (int nb = 0; nb < 2; ++nb) bfr[nb] = *(const bf16x8*)(sb + b_base + nb * 4096 + xo[ks]);
; #pragma unroll
;       for (int mb = 0; mb < 2; ++mb)
; #pragma unroll
;         for (int nb = 0; nb < 2; ++nb)
;           acc[mb][nb] = __builtin_amdgcn_mfma_f32_32x32x16_bf16(af[mb], bfr[nb], acc[mb][nb], 0, 0, 0);
;     }
;     WAIT_V0();
;     __syncthreads();
;   }
	global_load_lds_dwordx4 v[64:65], off
	s_mov_b32 m0, s85
	v_lshl_add_u64 v[64:65], v[66:67], 0, s[6:7]
	global_load_lds_dwordx4 v76, s[66:67]
	s_mov_b32 m0, s86
	v_mfma_f32_32x32x16_bf16 v[16:31], v[88:91], v[92:95], v[16:31]
	global_load_lds_dwordx4 v[64:65], off
	s_mov_b32 m0, s87
	v_lshl_add_u64 v[64:65], v[68:69], 0, s[6:7]
	global_load_lds_dwordx4 v77, s[66:67]
	s_mov_b32 m0, s88
	v_mfma_f32_32x32x16_bf16 v[0:15], v[88:91], v[96:99], v[0:15]
	global_load_lds_dwordx4 v[64:65], off
	s_mov_b32 m0, s89
	v_lshl_add_u64 v[64:65], v[70:71], 0, s[6:7]
	global_load_lds_dwordx4 v78, s[66:67]
	s_mov_b32 m0, s90
	v_readlane_b32 s86, v254, 58
	global_load_lds_dwordx4 v[64:65], off
	s_mov_b32 m0, s91
	v_readlane_b32 s87, v254, 59
	global_load_lds_dwordx4 v84, s[66:67]
	ds_read_b128 v[64:67], v79
	ds_read_b128 v[68:71], v81 offset:16384
	ds_read_b128 v[88:91], v81 offset:20480
	s_waitcnt lgkmcnt(0)
	v_mfma_f32_32x32x16_bf16 v[48:63], v[64:67], v[68:71], v[48:63]
	v_mfma_f32_32x32x16_bf16 v[32:47], v[64:67], v[88:91], v[32:47]
	ds_read_b128 v[64:67], v79 offset:4096
	s_waitcnt lgkmcnt(0)
	v_mfma_f32_32x32x16_bf16 v[16:31], v[64:67], v[68:71], v[16:31]
	v_mfma_f32_32x32x16_bf16 v[0:15], v[64:67], v[88:91], v[0:15]
	ds_read_b128 v[64:67], v80
	ds_read_b128 v[68:71], v83 offset:16384
	ds_read_b128 v[88:91], v83 offset:20480
	s_waitcnt lgkmcnt(0)
	v_mfma_f32_32x32x16_bf16 v[48:63], v[64:67], v[68:71], v[48:63]
	v_mfma_f32_32x32x16_bf16 v[32:47], v[64:67], v[88:91], v[32:47]
	ds_read_b128 v[64:67], v80 offset:4096
	s_waitcnt lgkmcnt(0)
	v_mfma_f32_32x32x16_bf16 v[16:31], v[64:67], v[68:71], v[16:31]
	v_mfma_f32_32x32x16_bf16 v[0:15], v[64:67], v[88:91], v[0:15]
	ds_read_b128 v[64:67], v82
	ds_read_b128 v[68:71], v85 offset:16384
	ds_read_b128 v[88:91], v85 offset:20480
	s_waitcnt lgkmcnt(0)
	v_mfma_f32_32x32x16_bf16 v[48:63], v[64:67], v[68:71], v[48:63]
	v_mfma_f32_32x32x16_bf16 v[32:47], v[64:67], v[88:91], v[32:47]
	ds_read_b128 v[64:67], v82 offset:4096
	s_waitcnt lgkmcnt(0)
	v_mfma_f32_32x32x16_bf16 v[16:31], v[64:67], v[68:71], v[16:31]
	v_mfma_f32_32x32x16_bf16 v[0:15], v[64:67], v[88:91], v[0:15]
	ds_read_b128 v[64:67], v86
	ds_read_b128 v[68:71], v87 offset:16384
	ds_read_b128 v[88:91], v87 offset:20480
	ds_read_b128 v[144:147], v86 offset:4096
	s_waitcnt vmcnt(0)
	s_waitcnt vmcnt(0) lgkmcnt(0)
	s_barrier
	v_mfma_f32_32x32x16_bf16 v[48:63], v[64:67], v[68:71], v[48:63]
	v_mfma_f32_32x32x16_bf16 v[32:47], v[64:67], v[88:91], v[32:47]
	v_mfma_f32_32x32x16_bf16 v[16:31], v[144:147], v[68:71], v[16:31]
	v_mfma_f32_32x32x16_bf16 v[0:15], v[144:147], v[88:91], v[0:15]
	ds_read_b128 v[64:67], v79 offset:32768
	ds_read_b128 v[68:71], v81 offset:49152
	ds_read_b128 v[88:91], v81 offset:53248
	s_waitcnt lgkmcnt(1)
	v_mfma_f32_32x32x16_bf16 v[48:63], v[64:67], v[68:71], v[48:63]
	s_waitcnt lgkmcnt(0)
	v_mfma_f32_32x32x16_bf16 v[32:47], v[64:67], v[88:91], v[32:47]
	ds_read_b128 v[64:67], v79 offset:36864
	s_waitcnt lgkmcnt(0)
	v_mfma_f32_32x32x16_bf16 v[16:31], v[64:67], v[68:71], v[16:31]
	v_mfma_f32_32x32x16_bf16 v[0:15], v[64:67], v[88:91], v[0:15]
	ds_read_b128 v[64:67], v80 offset:32768
	ds_read_b128 v[68:71], v83 offset:49152
	ds_read_b128 v[76:79], v83 offset:53248
	s_waitcnt lgkmcnt(1)
	v_mfma_f32_32x32x16_bf16 v[48:63], v[64:67], v[68:71], v[48:63]
	s_waitcnt lgkmcnt(0)
	v_mfma_f32_32x32x16_bf16 v[32:47], v[64:67], v[76:79], v[32:47]
	ds_read_b128 v[64:67], v80 offset:36864
	s_waitcnt lgkmcnt(0)
	v_mfma_f32_32x32x16_bf16 v[16:31], v[64:67], v[68:71], v[16:31]
	v_mfma_f32_32x32x16_bf16 v[0:15], v[64:67], v[76:79], v[0:15]
	ds_read_b128 v[64:67], v82 offset:32768
	ds_read_b128 v[68:71], v85 offset:49152
	ds_read_b128 v[76:79], v85 offset:53248
	s_waitcnt lgkmcnt(1)
	v_mfma_f32_32x32x16_bf16 v[48:63], v[64:67], v[68:71], v[48:63]
	s_waitcnt lgkmcnt(0)
	v_mfma_f32_32x32x16_bf16 v[32:47], v[64:67], v[76:79], v[32:47]
	ds_read_b128 v[64:67], v82 offset:36864
	s_waitcnt lgkmcnt(0)
	v_mfma_f32_32x32x16_bf16 v[16:31], v[64:67], v[68:71], v[16:31]
	ds_read_b128 v[68:71], v87 offset:53248
	ds_read_b128 v[80:83], v87 offset:49152
	ds_read_b128 v[88:91], v86 offset:36864
	ds_read_b128 v[84:87], v86 offset:32768
	s_waitcnt vmcnt(0)
	s_waitcnt lgkmcnt(0)
	s_barrier
; template <class F>
; DI void epi_foreach(const f32x16 (&acc)[2][2], F f) {
;     ...
;       for (int r = 0; r < 16; ++r) {
;         const int row = wm * 64 + mb * 32 + (r & 3) + 8 * (r >> 2) + 4 * (lane >> 5);
;         const int col = wn * 64 + nb * 32 + (lane & 31);
;         f(row, col, acc[mb][nb][r]);
;         if ((r & 7) == 7) __builtin_amdgcn_sched_barrier(0);
; DI void phase_up(const Params& P, int layer, char* smem) {
;     ...
;     epi_foreach(acc, [&](int row, int col, float v) __attribute__((always_inline)) { Cs[row * 136 + col] = f2bf(v); });
;     __syncthreads();
;     {
;       const int col = tid & 63, rb = tid >> 6;
;       const int cv = nt * 64 + col, cg_ = DFF + nt * 64 + col;
;       const float w0v = cw[cv], w1v = cw[5632 + cv], w2v = cw[2 * 5632 + cv], bv = cb[cv];
;       const float w0g = cw[cg_], w1g = cw[5632 + cg_], w2g = cw[2 * 5632 + cg_], bgt = cb[cg_];
;       for (int r = 2 + rb; r < 128; r += 4) {
	v_mfma_f32_32x32x16_bf16 v[48:63], v[84:87], v[80:83], v[48:63]
	v_mfma_f32_32x32x16_bf16 v[0:15], v[64:67], v[76:79], v[0:15]
	v_mov_b32_e32 v64, v161
	v_mov_b32_e32 v65, v161
	v_lshrrev_b32_e32 v67, 3, v64
	v_and_b32_e32 v67, 4, v67
	v_lshrrev_b32_e32 v66, 1, v65
	v_and_b32_e32 v64, 31, v64
	v_and_or_b32 v64, v65, 64, v64
	v_and_or_b32 v65, v66, s3, v67
	v_mul_lo_u32 v65, v65, s97
	s_nop 1
	v_cvt_pk_bf16_f32 v48, v48, s0
	v_lshl_add_u32 v64, v64, 1, v65
	ds_write_b16 v64, v48
	v_cvt_pk_bf16_f32 v48, v49, s0
	ds_write_b16 v64, v48 offset:272
	v_cvt_pk_bf16_f32 v48, v50, s0
	ds_write_b16 v64, v48 offset:544
	v_cvt_pk_bf16_f32 v48, v51, s0
	ds_write_b16 v64, v48 offset:816
	v_cvt_pk_bf16_f32 v48, v52, s0
	ds_write_b16 v64, v48 offset:2176
	v_cvt_pk_bf16_f32 v48, v53, s0
	ds_write_b16 v64, v48 offset:2448
	v_cvt_pk_bf16_f32 v48, v54, s0
	ds_write_b16 v64, v48 offset:2720
	v_cvt_pk_bf16_f32 v48, v55, s0
	v_mfma_f32_32x32x16_bf16 v[32:47], v[84:87], v[68:71], v[32:47]
	ds_write_b16 v64, v48 offset:2992
	v_mfma_f32_32x32x16_bf16 v[16:31], v[88:91], v[80:83], v[16:31]
	v_mfma_f32_32x32x16_bf16 v[0:15], v[88:91], v[68:71], v[0:15]
	v_cvt_pk_bf16_f32 v48, v56, s0
	ds_write_b16 v64, v48 offset:4352
	v_cvt_pk_bf16_f32 v48, v57, s0
	ds_write_b16 v64, v48 offset:4624
	v_cvt_pk_bf16_f32 v48, v58, s0
	ds_write_b16 v64, v48 offset:4896
	v_cvt_pk_bf16_f32 v48, v59, s0
	ds_write_b16 v64, v48 offset:5168
	v_cvt_pk_bf16_f32 v48, v60, s0
	ds_write_b16 v64, v48 offset:6528
	v_cvt_pk_bf16_f32 v48, v61, s0
	ds_write_b16 v64, v48 offset:6800
	v_cvt_pk_bf16_f32 v48, v62, s0
	ds_write_b16 v64, v48 offset:7072
	v_cvt_pk_bf16_f32 v48, v63, s0
	ds_write_b16 v64, v48 offset:7344
	v_cvt_pk_bf16_f32 v32, v32, s0
	ds_write_b16 v64, v32 offset:64
	v_cvt_pk_bf16_f32 v32, v33, s0
	ds_write_b16 v64, v32 offset:336
	v_cvt_pk_bf16_f32 v32, v34, s0
	ds_write_b16 v64, v32 offset:608
	v_cvt_pk_bf16_f32 v32, v35, s0
	ds_write_b16 v64, v32 offset:880
	v_cvt_pk_bf16_f32 v32, v36, s0
	ds_write_b16 v64, v32 offset:2240
	v_cvt_pk_bf16_f32 v32, v37, s0
	ds_write_b16 v64, v32 offset:2512
	v_cvt_pk_bf16_f32 v32, v38, s0
	ds_write_b16 v64, v32 offset:2784
	v_cvt_pk_bf16_f32 v32, v39, s0
	ds_write_b16 v64, v32 offset:3056
	v_cvt_pk_bf16_f32 v32, v40, s0
	ds_write_b16 v64, v32 offset:4416
	v_cvt_pk_bf16_f32 v32, v41, s0
	ds_write_b16 v64, v32 offset:4688
	v_cvt_pk_bf16_f32 v32, v42, s0
	ds_write_b16 v64, v32 offset:4960
	v_cvt_pk_bf16_f32 v32, v43, s0
	ds_write_b16 v64, v32 offset:5232
	v_cvt_pk_bf16_f32 v32, v44, s0
	ds_write_b16 v64, v32 offset:6592
	v_cvt_pk_bf16_f32 v32, v45, s0
	ds_write_b16 v64, v32 offset:6864
	v_cvt_pk_bf16_f32 v32, v46, s0
	ds_write_b16 v64, v32 offset:7136
	v_cvt_pk_bf16_f32 v32, v47, s0
	ds_write_b16 v64, v32 offset:7408
	v_cvt_pk_bf16_f32 v16, v16, s0
	ds_write_b16 v64, v16 offset:8704
	v_cvt_pk_bf16_f32 v16, v17, s0
	ds_write_b16 v64, v16 offset:8976
	v_cvt_pk_bf16_f32 v16, v18, s0
	ds_write_b16 v64, v16 offset:9248
	v_cvt_pk_bf16_f32 v16, v19, s0
	ds_write_b16 v64, v16 offset:9520
	v_cvt_pk_bf16_f32 v16, v20, s0
	ds_write_b16 v64, v16 offset:10880
	v_cvt_pk_bf16_f32 v16, v21, s0
	ds_write_b16 v64, v16 offset:11152
	v_cvt_pk_bf16_f32 v16, v22, s0
	ds_write_b16 v64, v16 offset:11424
	v_cvt_pk_bf16_f32 v16, v23, s0
	ds_write_b16 v64, v16 offset:11696
	v_cvt_pk_bf16_f32 v16, v24, s0
	ds_write_b16 v64, v16 offset:13056
	v_cvt_pk_bf16_f32 v16, v25, s0
	ds_write_b16 v64, v16 offset:13328
	v_cvt_pk_bf16_f32 v16, v26, s0
	ds_write_b16 v64, v16 offset:13600
	v_cvt_pk_bf16_f32 v16, v27, s0
	ds_write_b16 v64, v16 offset:13872
	v_cvt_pk_bf16_f32 v16, v28, s0
	ds_write_b16 v64, v16 offset:15232
	v_cvt_pk_bf16_f32 v16, v29, s0
	ds_write_b16 v64, v16 offset:15504
	v_cvt_pk_bf16_f32 v16, v30, s0
	ds_write_b16 v64, v16 offset:15776
	v_cvt_pk_bf16_f32 v16, v31, s0
	ds_write_b16 v64, v16 offset:16048
	v_cvt_pk_bf16_f32 v0, v0, s0
	ds_write_b16 v64, v0 offset:8768
	v_cvt_pk_bf16_f32 v0, v1, s0
	ds_write_b16 v64, v0 offset:9040
	v_cvt_pk_bf16_f32 v0, v2, s0
	ds_write_b16 v64, v0 offset:9312
	v_cvt_pk_bf16_f32 v0, v3, s0
	ds_write_b16 v64, v0 offset:9584
	v_cvt_pk_bf16_f32 v0, v4, s0
	ds_write_b16 v64, v0 offset:10944
	v_cvt_pk_bf16_f32 v0, v5, s0
	ds_write_b16 v64, v0 offset:11216
	v_cvt_pk_bf16_f32 v0, v6, s0
	ds_write_b16 v64, v0 offset:11488
	v_cvt_pk_bf16_f32 v0, v7, s0
	ds_write_b16 v64, v0 offset:11760
	v_cvt_pk_bf16_f32 v0, v8, s0
	ds_write_b16 v64, v0 offset:13120
	v_cvt_pk_bf16_f32 v0, v9, s0
	ds_write_b16 v64, v0 offset:13392
	v_cvt_pk_bf16_f32 v0, v10, s0
	ds_write_b16 v64, v0 offset:13664
	v_cvt_pk_bf16_f32 v0, v11, s0
	ds_write_b16 v64, v0 offset:13936
	v_cvt_pk_bf16_f32 v0, v12, s0
	ds_write_b16 v64, v0 offset:15296
	v_cvt_pk_bf16_f32 v0, v13, s0
	ds_write_b16 v64, v0 offset:15568
	v_cvt_pk_bf16_f32 v0, v14, s0
	ds_write_b16 v64, v0 offset:15840
	v_cvt_pk_bf16_f32 v0, v15, s0
	ds_write_b16 v64, v0 offset:16112
	s_waitcnt lgkmcnt(0)
	s_barrier
	s_and_saveexec_b64 s[18:19], s[40:41]
	s_mov_b32 s3, 0xb000
	s_cbranch_execz .LBB0_24
	v_add_u32_e32 v136, s21, v74
	v_lshlrev_b64 v[4:5], 2, v[136:137]
	v_lshl_add_u64 v[8:9], s[10:11], 0, v[4:5]
	v_or_b32_e32 v10, s21, v72
	v_lshlrev_b32_e32 v126, 1, v10
	v_lshl_add_u64 v[2:3], s[12:13], 0, v[4:5]
	v_add_co_u32_e32 v4, vcc, 0xb000, v8
	v_ashrrev_i32_e32 v11, 31, v10
	s_nop 0
	v_addc_co_u32_e32 v5, vcc, 0, v9, vcc
	v_lshl_add_u64 v[0:1], v[10:11], 1, s[86:87]
	v_add_co_u32_e32 v6, vcc, 0x5000, v8
	v_lshlrev_b64 v[10:11], 2, v[10:11]
	s_nop 0
	v_addc_co_u32_e32 v7, vcc, 0, v9, vcc
	v_lshl_add_u64 v[12:13], s[12:13], 0, v[10:11]
	v_lshl_add_u64 v[10:11], s[10:11], 0, v[10:11]
	global_load_dword v3, v[2:3], off
	s_mulk_i32 s20, 0x7e
	global_load_dword v5, v[4:5], off
	s_nop 0
	global_load_dword v7, v[6:7], off offset:2048
	s_nop 0
	global_load_dword v9, v[8:9], off
	s_mul_i32 s21, s68, 0x7a
	global_load_dword v2, v[12:13], off
	v_add_co_u32_e32 v12, vcc, s3, v10
	s_sub_i32 s29, s20, s21
	s_nop 0
	v_addc_co_u32_e32 v13, vcc, 0, v11, vcc
	global_load_dword v4, v[12:13], off
	v_add_co_u32_e32 v12, vcc, 0x5000, v10
	s_mov_b64 s[20:21], 0
	s_nop 0
	v_addc_co_u32_e32 v13, vcc, 0, v11, vcc
	global_load_dword v6, v[12:13], off offset:2048
	global_load_dword v8, v[10:11], off
	v_mov_b32_e32 v11, v73
	v_mul_u32_u24_e32 v10, 0x110, v73
	v_mov_b32_e32 v128, 0
	v_mov_b32_e32 v129, 0
	v_mov_b32_e32 v130, 0
	v_mov_b32_e32 v131, 0
	v_mov_b32_e32 v132, 0
	v_mov_b32_e32 v133, 0
	v_mov_b32_e32 v134, 0
	v_mov_b32_e32 v135, 0
	s_waitcnt vmcnt(0)
	v_readfirstlane_b32 s22, v73
	v_add_u32_e32 v10, v75, v10
	v_add_u32_e32 v127, 0x1600, v126
	s_lshl_b32 s22, s22, 1
	s_add_i32 s23, s29, s22
	s_mul_hi_i32 s21, s23, 0x1600
	s_mul_i32 s20, s23, 0x1600
	s_add_u32 s20, s20, s86
	s_addc_u32 s21, s21, s87
	s_setprio 2
	s_branch .LBB0_28

; DI float bf2f(unsigned short u) { return __uint_as_float(((unsigned)u) << 16); }
; DI void phase_up(const Params& P, int layer, char* smem) {
;     ...
;       for (int r = 2 + rb; r < 128; r += 4) {
;         const int tb = tb0 + r;
;         if (tb < S_) {
;           const float val = bv + w0v * bf2f(Cs[(r - 2) * 136 + col]) + w1v * bf2f(Cs[(r - 1) * 136 + col]) + w2v * bf2f(Cs[r * 136 + col]);
;           const float gat = bgt + w0g * bf2f(Cs[(r - 2) * 136 + 64 + col]) + w1g * bf2f(Cs[(r - 1) * 136 + 64 + col]) + w2g * bf2f(Cs[r * 136 + 64 + col]);
;           const float a = gat / (1.f + __expf(-gat)) * val;
;           ACT[(size_t)(b * S_ + tb) * DFF + cv] = f2bf(a);
;         }
;       }
.Lconv_skipB:
	s_add_i32 s22, s22, 8
	v_add_u32_e32 v10, 0x880, v10
	s_add_u32 s20, s20, 0xb000
	s_addc_u32 s21, s21, 0
	s_cmpk_gt_i32 s22, 0x7d
	s_cbranch_scc0 .LBB0_28
	s_setprio 0
	s_branch .LBB0_24
